# scan y-store without exec toggling: the three non-writing lanes of each quad use an out-of-range LDS address (write dropped by hardware)
# baseline (speedup 1.0000x reference)
; #define SC_GET(X, t) do { const float* p = rec + (t) * 320; w##X = *(const f32x4*)p; a##X = *(const f32x4*)(p + 4); b##X = *(const f32x4*)(p + 8); k##X = *(const f32x4*)(p + 12); q##X = *(const f32x4*)(p + 16); \
;                 v##X = *(const f32x4*)(VVa + (t) * 64); } while (0)
; DI void scan_phase(unsigned char* lds, const Ctx& a, const Op& d, const int variant) {
;     ...
;             } else if (!(variant & 1)) {
;                 const float* base = (const float*)(lds + bi * SC_BUF);
;                 const float* rec = base + jg * 20; const float* VVa = base + 10240 + rA * 2;
;                 f32x4 wA, aA, bA, kA, qA, vA, wB, aB, bB, kB, qB, vB;
;     ...
;                 SC_GET(A, 0);
.LBB0_453:
	s_and_b32 s48, s47, 1
	s_and_saveexec_b64 s[10:11], s[8:9]
	s_xor_b64 s[10:11], exec, s[10:11]
	s_cbranch_execz .LBB0_466
	s_mul_i32 s30, s48, 0xd000
	v_add_u32_e32 v175, s30, v157
	v_add_u32_e32 v123, s30, v158
	v_mbcnt_lo_u32_b32 v176, -1, 0
	v_mbcnt_hi_u32_b32 v176, -1, v176
	v_and_b32_e32 v179, 3, v176
	v_bfe_u32 v177, v176, 3, 1
	v_bfe_u32 v176, v176, 2, 1
	v_lshlrev_b32_e32 v177, 7, v177
	v_lshl_add_u32 v176, v176, 2, v177
	v_add3_u32 v178, v169, s30, v176
	v_mov_b32_e32 v151, 0xff0000
	v_cmp_eq_u32_e32 vcc, 0, v179
	s_nop 1
	v_cndmask_b32_e32 v178, v151, v178, vcc
	v_cndmask_b32_e64 v176, 0, 1.0, s[4:5]
	v_mov_b32_e32 v177, v176
	s_mov_b32 s34, 0x11111111
	s_mov_b32 s35, 0x11111111
	ds_read_b128 v[40:43], v175
	ds_read_b128 v[44:47], v175 offset:16
	ds_read_b128 v[48:51], v175 offset:32
	ds_read_b128 v[52:55], v175 offset:48
	ds_read_b128 v[56:59], v175 offset:64
	ds_read_b128 v[60:63], v123 offset:40960
	v_readfirstlane_b32 s39, v158
	s_nop 3
	s_lshr_b32 s39, s39, 6
	s_cmp_eq_u32 s39, 0
	s_cbranch_scc1 .Lscan_stag_done

; #define SC_GET(X, t) do { const float* p = rec + (t) * 320; w##X = *(const f32x4*)p; a##X = *(const f32x4*)(p + 4); b##X = *(const f32x4*)(p + 8); k##X = *(const f32x4*)(p + 12); q##X = *(const f32x4*)(p + 16); \
;                 v##X = *(const f32x4*)(VVa + (t) * 64); } while (0)
; DI void scan_phase(unsigned char* lds, const Ctx& a, const Op& d, const int variant) {
;     ...
;                 SC_GET(A, 0);
; #pragma unroll 2
;                 for (int t = 0; t < SC_T; t += 2) {
;                     SC_GET(B, t + 1);
;                     SC_STEP(A, t);
;                     if (t + 2 < SC_T) SC_GET(A, t + 2);
;                     SC_STEP(B, t + 1);
;                 }
.Lscan_steps:
	s_waitcnt lgkmcnt(1)
	ds_read_b128 v[72:75], v175 offset:1280
	ds_read_b128 v[76:79], v175 offset:1296
	ds_read_b128 v[80:83], v175 offset:1312
	ds_read_b128 v[84:87], v175 offset:1328
	ds_read_b128 v[88:91], v175 offset:1344
	ds_read_b128 v[92:95], v123 offset:41216
	v_pk_mul_f32 v[106:107], v[64:65], v[44:45] op_sel_hi:[1,0]
	v_pk_mul_f32 v[108:109], v[64:65], v[56:57] op_sel_hi:[1,0]
	v_pk_fma_f32 v[106:107], v[66:67], v[44:45], v[106:107] op_sel:[0,1,0]
	v_pk_fma_f32 v[108:109], v[66:67], v[56:57], v[108:109] op_sel:[0,1,0]
	v_pk_fma_f32 v[106:107], v[68:69], v[46:47], v[106:107] op_sel_hi:[1,0,1]
	v_pk_fma_f32 v[108:109], v[68:69], v[58:59], v[108:109] op_sel_hi:[1,0,1]
	v_pk_fma_f32 v[106:107], v[70:71], v[46:47], v[106:107] op_sel:[0,1,0]
	v_pk_fma_f32 v[108:109], v[70:71], v[58:59], v[108:109] op_sel:[0,1,0]
	v_pk_mul_f32 v[110:111], v[64:65], v[40:41] op_sel_hi:[1,0]
	v_add_f32_dpp v106, v106, v106 quad_perm:[1,0,3,2] row_mask:0xf bank_mask:0xf bound_ctrl:1
	v_add_f32_dpp v107, v107, v107 quad_perm:[1,0,3,2] row_mask:0xf bank_mask:0xf bound_ctrl:1
	v_pk_fma_f32 v[108:109], v[62:63], v[176:177], v[108:109]
	v_pk_mul_f32 v[112:113], v[66:67], v[40:41] op_sel:[0,1]
	v_add_f32_dpp v106, v106, v106 quad_perm:[2,3,0,1] row_mask:0xf bank_mask:0xf bound_ctrl:1
	v_add_f32_dpp v107, v107, v107 quad_perm:[2,3,0,1] row_mask:0xf bank_mask:0xf bound_ctrl:1
	v_add_f32_dpp v148, v108, v108 row_half_mirror row_mask:0xf bank_mask:0xf bound_ctrl:1
	v_add_f32_dpp v148, v109, v109 row_half_mirror row_mask:0xf bank_mask:0xa
	v_add_f32_dpp v106, v106, v106 row_half_mirror row_mask:0xf bank_mask:0xf bound_ctrl:1
	v_add_f32_dpp v107, v107, v107 row_half_mirror row_mask:0xf bank_mask:0xf bound_ctrl:1
	v_pk_mul_f32 v[144:145], v[68:69], v[42:43] op_sel_hi:[1,0]
	v_pk_mul_f32 v[146:147], v[70:71], v[42:43] op_sel:[0,1]
	v_add_f32_dpp v106, v106, v106 row_mirror row_mask:0xf bank_mask:0xf bound_ctrl:1
	v_add_f32_dpp v107, v107, v107 row_mirror row_mask:0xf bank_mask:0xf bound_ctrl:1
	v_pk_fma_f32 v[110:111], v[60:61], v[52:53], v[110:111] op_sel_hi:[1,0,1]
	v_pk_fma_f32 v[112:113], v[60:61], v[52:53], v[112:113] op_sel:[0,1,0]
	v_pk_fma_f32 v[144:145], v[60:61], v[54:55], v[144:145] op_sel_hi:[1,0,1]
	v_pk_fma_f32 v[146:147], v[60:61], v[54:55], v[146:147] op_sel:[0,1,0]
	v_pk_fma_f32 v[64:65], v[106:107], v[48:49], v[110:111] op_sel_hi:[1,0,1]
	v_pk_fma_f32 v[66:67], v[106:107], v[48:49], v[112:113] op_sel:[0,1,0]
	v_pk_fma_f32 v[68:69], v[106:107], v[50:51], v[144:145] op_sel_hi:[1,0,1]
	v_pk_fma_f32 v[70:71], v[106:107], v[50:51], v[146:147] op_sel:[0,1,0]
	s_waitcnt lgkmcnt(0)
	ds_read_b128 v[40:43], v175 offset:2560
	ds_read_b128 v[44:47], v175 offset:2576
	ds_read_b128 v[48:51], v175 offset:2592
	ds_read_b128 v[52:55], v175 offset:2608
	ds_read_b128 v[56:59], v175 offset:2624
	ds_read_b128 v[60:63], v123 offset:41472
	v_pk_mul_f32 v[106:107], v[64:65], v[76:77] op_sel_hi:[1,0]
	v_pk_mul_f32 v[108:109], v[64:65], v[88:89] op_sel_hi:[1,0]
	v_pk_fma_f32 v[106:107], v[66:67], v[76:77], v[106:107] op_sel:[0,1,0]
	v_pk_fma_f32 v[108:109], v[66:67], v[88:89], v[108:109] op_sel:[0,1,0]
	v_pk_fma_f32 v[106:107], v[68:69], v[78:79], v[106:107] op_sel_hi:[1,0,1]
	v_pk_fma_f32 v[108:109], v[68:69], v[90:91], v[108:109] op_sel_hi:[1,0,1]
	v_pk_fma_f32 v[106:107], v[70:71], v[78:79], v[106:107] op_sel:[0,1,0]
	v_pk_fma_f32 v[108:109], v[70:71], v[90:91], v[108:109] op_sel:[0,1,0]
	v_pk_mul_f32 v[110:111], v[64:65], v[72:73] op_sel_hi:[1,0]
	v_add_f32_dpp v106, v106, v106 quad_perm:[1,0,3,2] row_mask:0xf bank_mask:0xf bound_ctrl:1
	v_add_f32_dpp v107, v107, v107 quad_perm:[1,0,3,2] row_mask:0xf bank_mask:0xf bound_ctrl:1
	v_pk_fma_f32 v[108:109], v[94:95], v[176:177], v[108:109]
	v_pk_mul_f32 v[112:113], v[66:67], v[72:73] op_sel:[0,1]
	v_add_f32_dpp v106, v106, v106 quad_perm:[2,3,0,1] row_mask:0xf bank_mask:0xf bound_ctrl:1
	v_add_f32_dpp v107, v107, v107 quad_perm:[2,3,0,1] row_mask:0xf bank_mask:0xf bound_ctrl:1
	v_add_f32_dpp v149, v108, v108 row_half_mirror row_mask:0xf bank_mask:0xf bound_ctrl:1
	v_add_f32_dpp v149, v109, v109 row_half_mirror row_mask:0xf bank_mask:0xa
	v_add_f32_dpp v106, v106, v106 row_half_mirror row_mask:0xf bank_mask:0xf bound_ctrl:1
	v_add_f32_dpp v107, v107, v107 row_half_mirror row_mask:0xf bank_mask:0xf bound_ctrl:1
	v_pk_mul_f32 v[144:145], v[68:69], v[74:75] op_sel_hi:[1,0]
	v_pk_mul_f32 v[146:147], v[70:71], v[74:75] op_sel:[0,1]
	v_add_f32_dpp v150, v148, v148 row_ror:8 row_mask:0xf bank_mask:0xf bound_ctrl:1
	v_add_f32_dpp v150, v149, v149 row_ror:8 row_mask:0xf bank_mask:0xc
	v_add_f32_dpp v106, v106, v106 row_mirror row_mask:0xf bank_mask:0xf bound_ctrl:1
	v_add_f32_dpp v107, v107, v107 row_mirror row_mask:0xf bank_mask:0xf bound_ctrl:1
	v_pk_fma_f32 v[110:111], v[92:93], v[84:85], v[110:111] op_sel_hi:[1,0,1]
	v_pk_fma_f32 v[112:113], v[92:93], v[84:85], v[112:113] op_sel:[0,1,0]
	v_pk_fma_f32 v[144:145], v[92:93], v[86:87], v[144:145] op_sel_hi:[1,0,1]
	v_pk_fma_f32 v[146:147], v[92:93], v[86:87], v[146:147] op_sel:[0,1,0]
	v_add_f32_dpp v150, v150, v150 quad_perm:[1,0,3,2] row_mask:0xf bank_mask:0xf bound_ctrl:1
	v_pk_fma_f32 v[64:65], v[106:107], v[80:81], v[110:111] op_sel_hi:[1,0,1]
	v_pk_fma_f32 v[66:67], v[106:107], v[80:81], v[112:113] op_sel:[0,1,0]
	v_add_f32_dpp v150, v150, v150 quad_perm:[2,3,0,1] row_mask:0xf bank_mask:0xf bound_ctrl:1
	v_pk_fma_f32 v[68:69], v[106:107], v[82:83], v[144:145] op_sel_hi:[1,0,1]
	v_pk_fma_f32 v[70:71], v[106:107], v[82:83], v[146:147] op_sel:[0,1,0]
	ds_write_b32 v178, v150 offset:0
	s_waitcnt lgkmcnt(1)
; #define SC_GET(X, t) do { const float* p = rec + (t) * 320; w##X = *(const f32x4*)p; a##X = *(const f32x4*)(p + 4); b##X = *(const f32x4*)(p + 8); k##X = *(const f32x4*)(p + 12); q##X = *(const f32x4*)(p + 16); \
;                 v##X = *(const f32x4*)(VVa + (t) * 64); } while (0)
; DI void scan_phase(unsigned char* lds, const Ctx& a, const Op& d, const int variant) {
;     ...
;                 SC_GET(A, 0);
; #pragma unroll 2
;                 for (int t = 0; t < SC_T; t += 2) {
;                     SC_GET(B, t + 1);
;                     SC_STEP(A, t);
;                     if (t + 2 < SC_T) SC_GET(A, t + 2);
;                     SC_STEP(B, t + 1);
;                 }
	ds_read_b128 v[72:75], v175 offset:3840
	ds_read_b128 v[76:79], v175 offset:3856
	ds_read_b128 v[80:83], v175 offset:3872
	ds_read_b128 v[84:87], v175 offset:3888
	ds_read_b128 v[88:91], v175 offset:3904
	ds_read_b128 v[92:95], v123 offset:41728
	v_pk_mul_f32 v[106:107], v[64:65], v[44:45] op_sel_hi:[1,0]
	v_pk_mul_f32 v[108:109], v[64:65], v[56:57] op_sel_hi:[1,0]
	v_pk_fma_f32 v[106:107], v[66:67], v[44:45], v[106:107] op_sel:[0,1,0]
	v_pk_fma_f32 v[108:109], v[66:67], v[56:57], v[108:109] op_sel:[0,1,0]
	v_pk_fma_f32 v[106:107], v[68:69], v[46:47], v[106:107] op_sel_hi:[1,0,1]
	v_pk_fma_f32 v[108:109], v[68:69], v[58:59], v[108:109] op_sel_hi:[1,0,1]
	v_pk_fma_f32 v[106:107], v[70:71], v[46:47], v[106:107] op_sel:[0,1,0]
	v_pk_fma_f32 v[108:109], v[70:71], v[58:59], v[108:109] op_sel:[0,1,0]
	v_pk_mul_f32 v[110:111], v[64:65], v[40:41] op_sel_hi:[1,0]
	v_add_f32_dpp v106, v106, v106 quad_perm:[1,0,3,2] row_mask:0xf bank_mask:0xf bound_ctrl:1
	v_add_f32_dpp v107, v107, v107 quad_perm:[1,0,3,2] row_mask:0xf bank_mask:0xf bound_ctrl:1
	v_pk_fma_f32 v[108:109], v[62:63], v[176:177], v[108:109]
	v_pk_mul_f32 v[112:113], v[66:67], v[40:41] op_sel:[0,1]
	v_add_f32_dpp v106, v106, v106 quad_perm:[2,3,0,1] row_mask:0xf bank_mask:0xf bound_ctrl:1
	v_add_f32_dpp v107, v107, v107 quad_perm:[2,3,0,1] row_mask:0xf bank_mask:0xf bound_ctrl:1
	v_add_f32_dpp v148, v108, v108 row_half_mirror row_mask:0xf bank_mask:0xf bound_ctrl:1
	v_add_f32_dpp v148, v109, v109 row_half_mirror row_mask:0xf bank_mask:0xa
	v_add_f32_dpp v106, v106, v106 row_half_mirror row_mask:0xf bank_mask:0xf bound_ctrl:1
	v_add_f32_dpp v107, v107, v107 row_half_mirror row_mask:0xf bank_mask:0xf bound_ctrl:1
	v_pk_mul_f32 v[144:145], v[68:69], v[42:43] op_sel_hi:[1,0]
	v_pk_mul_f32 v[146:147], v[70:71], v[42:43] op_sel:[0,1]
	v_add_f32_dpp v106, v106, v106 row_mirror row_mask:0xf bank_mask:0xf bound_ctrl:1
	v_add_f32_dpp v107, v107, v107 row_mirror row_mask:0xf bank_mask:0xf bound_ctrl:1
	v_pk_fma_f32 v[110:111], v[60:61], v[52:53], v[110:111] op_sel_hi:[1,0,1]
	v_pk_fma_f32 v[112:113], v[60:61], v[52:53], v[112:113] op_sel:[0,1,0]
	v_pk_fma_f32 v[144:145], v[60:61], v[54:55], v[144:145] op_sel_hi:[1,0,1]
	v_pk_fma_f32 v[146:147], v[60:61], v[54:55], v[146:147] op_sel:[0,1,0]
	v_pk_fma_f32 v[64:65], v[106:107], v[48:49], v[110:111] op_sel_hi:[1,0,1]
	v_pk_fma_f32 v[66:67], v[106:107], v[48:49], v[112:113] op_sel:[0,1,0]
	v_pk_fma_f32 v[68:69], v[106:107], v[50:51], v[144:145] op_sel_hi:[1,0,1]
	v_pk_fma_f32 v[70:71], v[106:107], v[50:51], v[146:147] op_sel:[0,1,0]
	s_waitcnt lgkmcnt(0)
	ds_read_b128 v[40:43], v175 offset:5120
	ds_read_b128 v[44:47], v175 offset:5136
	ds_read_b128 v[48:51], v175 offset:5152
	ds_read_b128 v[52:55], v175 offset:5168
	ds_read_b128 v[56:59], v175 offset:5184
	ds_read_b128 v[60:63], v123 offset:41984
	v_pk_mul_f32 v[106:107], v[64:65], v[76:77] op_sel_hi:[1,0]
	v_pk_mul_f32 v[108:109], v[64:65], v[88:89] op_sel_hi:[1,0]
	v_pk_fma_f32 v[106:107], v[66:67], v[76:77], v[106:107] op_sel:[0,1,0]
	v_pk_fma_f32 v[108:109], v[66:67], v[88:89], v[108:109] op_sel:[0,1,0]
	v_pk_fma_f32 v[106:107], v[68:69], v[78:79], v[106:107] op_sel_hi:[1,0,1]
	v_pk_fma_f32 v[108:109], v[68:69], v[90:91], v[108:109] op_sel_hi:[1,0,1]
	v_pk_fma_f32 v[106:107], v[70:71], v[78:79], v[106:107] op_sel:[0,1,0]
	v_pk_fma_f32 v[108:109], v[70:71], v[90:91], v[108:109] op_sel:[0,1,0]
	v_pk_mul_f32 v[110:111], v[64:65], v[72:73] op_sel_hi:[1,0]
	v_add_f32_dpp v106, v106, v106 quad_perm:[1,0,3,2] row_mask:0xf bank_mask:0xf bound_ctrl:1
	v_add_f32_dpp v107, v107, v107 quad_perm:[1,0,3,2] row_mask:0xf bank_mask:0xf bound_ctrl:1
	v_pk_fma_f32 v[108:109], v[94:95], v[176:177], v[108:109]
	v_pk_mul_f32 v[112:113], v[66:67], v[72:73] op_sel:[0,1]
	v_add_f32_dpp v106, v106, v106 quad_perm:[2,3,0,1] row_mask:0xf bank_mask:0xf bound_ctrl:1
	v_add_f32_dpp v107, v107, v107 quad_perm:[2,3,0,1] row_mask:0xf bank_mask:0xf bound_ctrl:1
	v_add_f32_dpp v149, v108, v108 row_half_mirror row_mask:0xf bank_mask:0xf bound_ctrl:1
	v_add_f32_dpp v149, v109, v109 row_half_mirror row_mask:0xf bank_mask:0xa
	v_add_f32_dpp v106, v106, v106 row_half_mirror row_mask:0xf bank_mask:0xf bound_ctrl:1
	v_add_f32_dpp v107, v107, v107 row_half_mirror row_mask:0xf bank_mask:0xf bound_ctrl:1
	v_pk_mul_f32 v[144:145], v[68:69], v[74:75] op_sel_hi:[1,0]
	v_pk_mul_f32 v[146:147], v[70:71], v[74:75] op_sel:[0,1]
	v_add_f32_dpp v150, v148, v148 row_ror:8 row_mask:0xf bank_mask:0xf bound_ctrl:1
	v_add_f32_dpp v150, v149, v149 row_ror:8 row_mask:0xf bank_mask:0xc
	v_add_f32_dpp v106, v106, v106 row_mirror row_mask:0xf bank_mask:0xf bound_ctrl:1
	v_add_f32_dpp v107, v107, v107 row_mirror row_mask:0xf bank_mask:0xf bound_ctrl:1
	v_pk_fma_f32 v[110:111], v[92:93], v[84:85], v[110:111] op_sel_hi:[1,0,1]
	v_pk_fma_f32 v[112:113], v[92:93], v[84:85], v[112:113] op_sel:[0,1,0]
	v_pk_fma_f32 v[144:145], v[92:93], v[86:87], v[144:145] op_sel_hi:[1,0,1]
	v_pk_fma_f32 v[146:147], v[92:93], v[86:87], v[146:147] op_sel:[0,1,0]
	v_add_f32_dpp v150, v150, v150 quad_perm:[1,0,3,2] row_mask:0xf bank_mask:0xf bound_ctrl:1
	v_pk_fma_f32 v[64:65], v[106:107], v[80:81], v[110:111] op_sel_hi:[1,0,1]
	v_pk_fma_f32 v[66:67], v[106:107], v[80:81], v[112:113] op_sel:[0,1,0]
	v_add_f32_dpp v150, v150, v150 quad_perm:[2,3,0,1] row_mask:0xf bank_mask:0xf bound_ctrl:1
	v_pk_fma_f32 v[68:69], v[106:107], v[82:83], v[144:145] op_sel_hi:[1,0,1]
	v_pk_fma_f32 v[70:71], v[106:107], v[82:83], v[146:147] op_sel:[0,1,0]
	ds_write_b32 v178, v150 offset:256
	s_waitcnt lgkmcnt(1)
; #define SC_GET(X, t) do { const float* p = rec + (t) * 320; w##X = *(const f32x4*)p; a##X = *(const f32x4*)(p + 4); b##X = *(const f32x4*)(p + 8); k##X = *(const f32x4*)(p + 12); q##X = *(const f32x4*)(p + 16); \
;                 v##X = *(const f32x4*)(VVa + (t) * 64); } while (0)
; DI void scan_phase(unsigned char* lds, const Ctx& a, const Op& d, const int variant) {
;     ...
;                 SC_GET(A, 0);
; #pragma unroll 2
;                 for (int t = 0; t < SC_T; t += 2) {
;                     SC_GET(B, t + 1);
;                     SC_STEP(A, t);
;                     if (t + 2 < SC_T) SC_GET(A, t + 2);
;                     SC_STEP(B, t + 1);
;                 }
	ds_read_b128 v[72:75], v175 offset:6400
	ds_read_b128 v[76:79], v175 offset:6416
	ds_read_b128 v[80:83], v175 offset:6432
	ds_read_b128 v[84:87], v175 offset:6448
	ds_read_b128 v[88:91], v175 offset:6464
	ds_read_b128 v[92:95], v123 offset:42240
	v_pk_mul_f32 v[106:107], v[64:65], v[44:45] op_sel_hi:[1,0]
	v_pk_mul_f32 v[108:109], v[64:65], v[56:57] op_sel_hi:[1,0]
	v_pk_fma_f32 v[106:107], v[66:67], v[44:45], v[106:107] op_sel:[0,1,0]
	v_pk_fma_f32 v[108:109], v[66:67], v[56:57], v[108:109] op_sel:[0,1,0]
	v_pk_fma_f32 v[106:107], v[68:69], v[46:47], v[106:107] op_sel_hi:[1,0,1]
	v_pk_fma_f32 v[108:109], v[68:69], v[58:59], v[108:109] op_sel_hi:[1,0,1]
	v_pk_fma_f32 v[106:107], v[70:71], v[46:47], v[106:107] op_sel:[0,1,0]
	v_pk_fma_f32 v[108:109], v[70:71], v[58:59], v[108:109] op_sel:[0,1,0]
	v_pk_mul_f32 v[110:111], v[64:65], v[40:41] op_sel_hi:[1,0]
	v_add_f32_dpp v106, v106, v106 quad_perm:[1,0,3,2] row_mask:0xf bank_mask:0xf bound_ctrl:1
	v_add_f32_dpp v107, v107, v107 quad_perm:[1,0,3,2] row_mask:0xf bank_mask:0xf bound_ctrl:1
	v_pk_fma_f32 v[108:109], v[62:63], v[176:177], v[108:109]
	v_pk_mul_f32 v[112:113], v[66:67], v[40:41] op_sel:[0,1]
	v_add_f32_dpp v106, v106, v106 quad_perm:[2,3,0,1] row_mask:0xf bank_mask:0xf bound_ctrl:1
	v_add_f32_dpp v107, v107, v107 quad_perm:[2,3,0,1] row_mask:0xf bank_mask:0xf bound_ctrl:1
	v_add_f32_dpp v148, v108, v108 row_half_mirror row_mask:0xf bank_mask:0xf bound_ctrl:1
	v_add_f32_dpp v148, v109, v109 row_half_mirror row_mask:0xf bank_mask:0xa
	v_add_f32_dpp v106, v106, v106 row_half_mirror row_mask:0xf bank_mask:0xf bound_ctrl:1
	v_add_f32_dpp v107, v107, v107 row_half_mirror row_mask:0xf bank_mask:0xf bound_ctrl:1
	v_pk_mul_f32 v[144:145], v[68:69], v[42:43] op_sel_hi:[1,0]
	v_pk_mul_f32 v[146:147], v[70:71], v[42:43] op_sel:[0,1]
	v_add_f32_dpp v106, v106, v106 row_mirror row_mask:0xf bank_mask:0xf bound_ctrl:1
	v_add_f32_dpp v107, v107, v107 row_mirror row_mask:0xf bank_mask:0xf bound_ctrl:1
	v_pk_fma_f32 v[110:111], v[60:61], v[52:53], v[110:111] op_sel_hi:[1,0,1]
	v_pk_fma_f32 v[112:113], v[60:61], v[52:53], v[112:113] op_sel:[0,1,0]
	v_pk_fma_f32 v[144:145], v[60:61], v[54:55], v[144:145] op_sel_hi:[1,0,1]
	v_pk_fma_f32 v[146:147], v[60:61], v[54:55], v[146:147] op_sel:[0,1,0]
	v_pk_fma_f32 v[64:65], v[106:107], v[48:49], v[110:111] op_sel_hi:[1,0,1]
	v_pk_fma_f32 v[66:67], v[106:107], v[48:49], v[112:113] op_sel:[0,1,0]
	v_pk_fma_f32 v[68:69], v[106:107], v[50:51], v[144:145] op_sel_hi:[1,0,1]
	v_pk_fma_f32 v[70:71], v[106:107], v[50:51], v[146:147] op_sel:[0,1,0]
	s_waitcnt lgkmcnt(0)
	ds_read_b128 v[40:43], v175 offset:7680
	ds_read_b128 v[44:47], v175 offset:7696
	ds_read_b128 v[48:51], v175 offset:7712
	ds_read_b128 v[52:55], v175 offset:7728
	ds_read_b128 v[56:59], v175 offset:7744
	ds_read_b128 v[60:63], v123 offset:42496
	v_pk_mul_f32 v[106:107], v[64:65], v[76:77] op_sel_hi:[1,0]
	v_pk_mul_f32 v[108:109], v[64:65], v[88:89] op_sel_hi:[1,0]
	v_pk_fma_f32 v[106:107], v[66:67], v[76:77], v[106:107] op_sel:[0,1,0]
	v_pk_fma_f32 v[108:109], v[66:67], v[88:89], v[108:109] op_sel:[0,1,0]
	v_pk_fma_f32 v[106:107], v[68:69], v[78:79], v[106:107] op_sel_hi:[1,0,1]
	v_pk_fma_f32 v[108:109], v[68:69], v[90:91], v[108:109] op_sel_hi:[1,0,1]
	v_pk_fma_f32 v[106:107], v[70:71], v[78:79], v[106:107] op_sel:[0,1,0]
	v_pk_fma_f32 v[108:109], v[70:71], v[90:91], v[108:109] op_sel:[0,1,0]
	v_pk_mul_f32 v[110:111], v[64:65], v[72:73] op_sel_hi:[1,0]
	v_add_f32_dpp v106, v106, v106 quad_perm:[1,0,3,2] row_mask:0xf bank_mask:0xf bound_ctrl:1
	v_add_f32_dpp v107, v107, v107 quad_perm:[1,0,3,2] row_mask:0xf bank_mask:0xf bound_ctrl:1
	v_pk_fma_f32 v[108:109], v[94:95], v[176:177], v[108:109]
	v_pk_mul_f32 v[112:113], v[66:67], v[72:73] op_sel:[0,1]
	v_add_f32_dpp v106, v106, v106 quad_perm:[2,3,0,1] row_mask:0xf bank_mask:0xf bound_ctrl:1
	v_add_f32_dpp v107, v107, v107 quad_perm:[2,3,0,1] row_mask:0xf bank_mask:0xf bound_ctrl:1
	v_add_f32_dpp v149, v108, v108 row_half_mirror row_mask:0xf bank_mask:0xf bound_ctrl:1
	v_add_f32_dpp v149, v109, v109 row_half_mirror row_mask:0xf bank_mask:0xa
	v_add_f32_dpp v106, v106, v106 row_half_mirror row_mask:0xf bank_mask:0xf bound_ctrl:1
	v_add_f32_dpp v107, v107, v107 row_half_mirror row_mask:0xf bank_mask:0xf bound_ctrl:1
	v_pk_mul_f32 v[144:145], v[68:69], v[74:75] op_sel_hi:[1,0]
	v_pk_mul_f32 v[146:147], v[70:71], v[74:75] op_sel:[0,1]
	v_add_f32_dpp v150, v148, v148 row_ror:8 row_mask:0xf bank_mask:0xf bound_ctrl:1
	v_add_f32_dpp v150, v149, v149 row_ror:8 row_mask:0xf bank_mask:0xc
	v_add_f32_dpp v106, v106, v106 row_mirror row_mask:0xf bank_mask:0xf bound_ctrl:1
	v_add_f32_dpp v107, v107, v107 row_mirror row_mask:0xf bank_mask:0xf bound_ctrl:1
	v_pk_fma_f32 v[110:111], v[92:93], v[84:85], v[110:111] op_sel_hi:[1,0,1]
	v_pk_fma_f32 v[112:113], v[92:93], v[84:85], v[112:113] op_sel:[0,1,0]
	v_pk_fma_f32 v[144:145], v[92:93], v[86:87], v[144:145] op_sel_hi:[1,0,1]
	v_pk_fma_f32 v[146:147], v[92:93], v[86:87], v[146:147] op_sel:[0,1,0]
	v_add_f32_dpp v150, v150, v150 quad_perm:[1,0,3,2] row_mask:0xf bank_mask:0xf bound_ctrl:1
	v_pk_fma_f32 v[64:65], v[106:107], v[80:81], v[110:111] op_sel_hi:[1,0,1]
	v_pk_fma_f32 v[66:67], v[106:107], v[80:81], v[112:113] op_sel:[0,1,0]
	v_add_f32_dpp v150, v150, v150 quad_perm:[2,3,0,1] row_mask:0xf bank_mask:0xf bound_ctrl:1
	v_pk_fma_f32 v[68:69], v[106:107], v[82:83], v[144:145] op_sel_hi:[1,0,1]
	v_pk_fma_f32 v[70:71], v[106:107], v[82:83], v[146:147] op_sel:[0,1,0]
	ds_write_b32 v178, v150 offset:512
	s_waitcnt lgkmcnt(1)
; #define SC_GET(X, t) do { const float* p = rec + (t) * 320; w##X = *(const f32x4*)p; a##X = *(const f32x4*)(p + 4); b##X = *(const f32x4*)(p + 8); k##X = *(const f32x4*)(p + 12); q##X = *(const f32x4*)(p + 16); \
;                 v##X = *(const f32x4*)(VVa + (t) * 64); } while (0)
; DI void scan_phase(unsigned char* lds, const Ctx& a, const Op& d, const int variant) {
;     ...
;                 SC_GET(A, 0);
; #pragma unroll 2
;                 for (int t = 0; t < SC_T; t += 2) {
;                     SC_GET(B, t + 1);
;                     SC_STEP(A, t);
;                     if (t + 2 < SC_T) SC_GET(A, t + 2);
;                     SC_STEP(B, t + 1);
;                 }
	ds_read_b128 v[72:75], v175 offset:8960
	ds_read_b128 v[76:79], v175 offset:8976
	ds_read_b128 v[80:83], v175 offset:8992
	ds_read_b128 v[84:87], v175 offset:9008
	ds_read_b128 v[88:91], v175 offset:9024
	ds_read_b128 v[92:95], v123 offset:42752
	v_pk_mul_f32 v[106:107], v[64:65], v[44:45] op_sel_hi:[1,0]
	v_pk_mul_f32 v[108:109], v[64:65], v[56:57] op_sel_hi:[1,0]
	v_pk_fma_f32 v[106:107], v[66:67], v[44:45], v[106:107] op_sel:[0,1,0]
	v_pk_fma_f32 v[108:109], v[66:67], v[56:57], v[108:109] op_sel:[0,1,0]
	v_pk_fma_f32 v[106:107], v[68:69], v[46:47], v[106:107] op_sel_hi:[1,0,1]
	v_pk_fma_f32 v[108:109], v[68:69], v[58:59], v[108:109] op_sel_hi:[1,0,1]
	v_pk_fma_f32 v[106:107], v[70:71], v[46:47], v[106:107] op_sel:[0,1,0]
	v_pk_fma_f32 v[108:109], v[70:71], v[58:59], v[108:109] op_sel:[0,1,0]
	v_pk_mul_f32 v[110:111], v[64:65], v[40:41] op_sel_hi:[1,0]
	v_add_f32_dpp v106, v106, v106 quad_perm:[1,0,3,2] row_mask:0xf bank_mask:0xf bound_ctrl:1
	v_add_f32_dpp v107, v107, v107 quad_perm:[1,0,3,2] row_mask:0xf bank_mask:0xf bound_ctrl:1
	v_pk_fma_f32 v[108:109], v[62:63], v[176:177], v[108:109]
	v_pk_mul_f32 v[112:113], v[66:67], v[40:41] op_sel:[0,1]
	v_add_f32_dpp v106, v106, v106 quad_perm:[2,3,0,1] row_mask:0xf bank_mask:0xf bound_ctrl:1
	v_add_f32_dpp v107, v107, v107 quad_perm:[2,3,0,1] row_mask:0xf bank_mask:0xf bound_ctrl:1
	v_add_f32_dpp v148, v108, v108 row_half_mirror row_mask:0xf bank_mask:0xf bound_ctrl:1
	v_add_f32_dpp v148, v109, v109 row_half_mirror row_mask:0xf bank_mask:0xa
	v_add_f32_dpp v106, v106, v106 row_half_mirror row_mask:0xf bank_mask:0xf bound_ctrl:1
	v_add_f32_dpp v107, v107, v107 row_half_mirror row_mask:0xf bank_mask:0xf bound_ctrl:1
	v_pk_mul_f32 v[144:145], v[68:69], v[42:43] op_sel_hi:[1,0]
	v_pk_mul_f32 v[146:147], v[70:71], v[42:43] op_sel:[0,1]
	v_add_f32_dpp v106, v106, v106 row_mirror row_mask:0xf bank_mask:0xf bound_ctrl:1
	v_add_f32_dpp v107, v107, v107 row_mirror row_mask:0xf bank_mask:0xf bound_ctrl:1
	v_pk_fma_f32 v[110:111], v[60:61], v[52:53], v[110:111] op_sel_hi:[1,0,1]
	v_pk_fma_f32 v[112:113], v[60:61], v[52:53], v[112:113] op_sel:[0,1,0]
	v_pk_fma_f32 v[144:145], v[60:61], v[54:55], v[144:145] op_sel_hi:[1,0,1]
	v_pk_fma_f32 v[146:147], v[60:61], v[54:55], v[146:147] op_sel:[0,1,0]
	v_pk_fma_f32 v[64:65], v[106:107], v[48:49], v[110:111] op_sel_hi:[1,0,1]
	v_pk_fma_f32 v[66:67], v[106:107], v[48:49], v[112:113] op_sel:[0,1,0]
	v_pk_fma_f32 v[68:69], v[106:107], v[50:51], v[144:145] op_sel_hi:[1,0,1]
	v_pk_fma_f32 v[70:71], v[106:107], v[50:51], v[146:147] op_sel:[0,1,0]
	s_waitcnt lgkmcnt(0)
	ds_read_b128 v[40:43], v175 offset:10240
	ds_read_b128 v[44:47], v175 offset:10256
	ds_read_b128 v[48:51], v175 offset:10272
	ds_read_b128 v[52:55], v175 offset:10288
	ds_read_b128 v[56:59], v175 offset:10304
	ds_read_b128 v[60:63], v123 offset:43008
	v_pk_mul_f32 v[106:107], v[64:65], v[76:77] op_sel_hi:[1,0]
	v_pk_mul_f32 v[108:109], v[64:65], v[88:89] op_sel_hi:[1,0]
	v_pk_fma_f32 v[106:107], v[66:67], v[76:77], v[106:107] op_sel:[0,1,0]
	v_pk_fma_f32 v[108:109], v[66:67], v[88:89], v[108:109] op_sel:[0,1,0]
	v_pk_fma_f32 v[106:107], v[68:69], v[78:79], v[106:107] op_sel_hi:[1,0,1]
	v_pk_fma_f32 v[108:109], v[68:69], v[90:91], v[108:109] op_sel_hi:[1,0,1]
	v_pk_fma_f32 v[106:107], v[70:71], v[78:79], v[106:107] op_sel:[0,1,0]
	v_pk_fma_f32 v[108:109], v[70:71], v[90:91], v[108:109] op_sel:[0,1,0]
	v_pk_mul_f32 v[110:111], v[64:65], v[72:73] op_sel_hi:[1,0]
	v_add_f32_dpp v106, v106, v106 quad_perm:[1,0,3,2] row_mask:0xf bank_mask:0xf bound_ctrl:1
	v_add_f32_dpp v107, v107, v107 quad_perm:[1,0,3,2] row_mask:0xf bank_mask:0xf bound_ctrl:1
	v_pk_fma_f32 v[108:109], v[94:95], v[176:177], v[108:109]
	v_pk_mul_f32 v[112:113], v[66:67], v[72:73] op_sel:[0,1]
	v_add_f32_dpp v106, v106, v106 quad_perm:[2,3,0,1] row_mask:0xf bank_mask:0xf bound_ctrl:1
	v_add_f32_dpp v107, v107, v107 quad_perm:[2,3,0,1] row_mask:0xf bank_mask:0xf bound_ctrl:1
	v_add_f32_dpp v149, v108, v108 row_half_mirror row_mask:0xf bank_mask:0xf bound_ctrl:1
	v_add_f32_dpp v149, v109, v109 row_half_mirror row_mask:0xf bank_mask:0xa
	v_add_f32_dpp v106, v106, v106 row_half_mirror row_mask:0xf bank_mask:0xf bound_ctrl:1
	v_add_f32_dpp v107, v107, v107 row_half_mirror row_mask:0xf bank_mask:0xf bound_ctrl:1
	v_pk_mul_f32 v[144:145], v[68:69], v[74:75] op_sel_hi:[1,0]
	v_pk_mul_f32 v[146:147], v[70:71], v[74:75] op_sel:[0,1]
	v_add_f32_dpp v150, v148, v148 row_ror:8 row_mask:0xf bank_mask:0xf bound_ctrl:1
	v_add_f32_dpp v150, v149, v149 row_ror:8 row_mask:0xf bank_mask:0xc
	v_add_f32_dpp v106, v106, v106 row_mirror row_mask:0xf bank_mask:0xf bound_ctrl:1
	v_add_f32_dpp v107, v107, v107 row_mirror row_mask:0xf bank_mask:0xf bound_ctrl:1
	v_pk_fma_f32 v[110:111], v[92:93], v[84:85], v[110:111] op_sel_hi:[1,0,1]
	v_pk_fma_f32 v[112:113], v[92:93], v[84:85], v[112:113] op_sel:[0,1,0]
	v_pk_fma_f32 v[144:145], v[92:93], v[86:87], v[144:145] op_sel_hi:[1,0,1]
	v_pk_fma_f32 v[146:147], v[92:93], v[86:87], v[146:147] op_sel:[0,1,0]
	v_add_f32_dpp v150, v150, v150 quad_perm:[1,0,3,2] row_mask:0xf bank_mask:0xf bound_ctrl:1
	v_pk_fma_f32 v[64:65], v[106:107], v[80:81], v[110:111] op_sel_hi:[1,0,1]
	v_pk_fma_f32 v[66:67], v[106:107], v[80:81], v[112:113] op_sel:[0,1,0]
	v_add_f32_dpp v150, v150, v150 quad_perm:[2,3,0,1] row_mask:0xf bank_mask:0xf bound_ctrl:1
	v_pk_fma_f32 v[68:69], v[106:107], v[82:83], v[144:145] op_sel_hi:[1,0,1]
	v_pk_fma_f32 v[70:71], v[106:107], v[82:83], v[146:147] op_sel:[0,1,0]
	ds_write_b32 v178, v150 offset:768
	s_waitcnt lgkmcnt(1)
; #define SC_GET(X, t) do { const float* p = rec + (t) * 320; w##X = *(const f32x4*)p; a##X = *(const f32x4*)(p + 4); b##X = *(const f32x4*)(p + 8); k##X = *(const f32x4*)(p + 12); q##X = *(const f32x4*)(p + 16); \
;                 v##X = *(const f32x4*)(VVa + (t) * 64); } while (0)
; DI void scan_phase(unsigned char* lds, const Ctx& a, const Op& d, const int variant) {
;     ...
;                 SC_GET(A, 0);
; #pragma unroll 2
;                 for (int t = 0; t < SC_T; t += 2) {
;                     SC_GET(B, t + 1);
;                     SC_STEP(A, t);
;                     if (t + 2 < SC_T) SC_GET(A, t + 2);
;                     SC_STEP(B, t + 1);
;                 }
	ds_read_b128 v[72:75], v175 offset:11520
	ds_read_b128 v[76:79], v175 offset:11536
	ds_read_b128 v[80:83], v175 offset:11552
	ds_read_b128 v[84:87], v175 offset:11568
	ds_read_b128 v[88:91], v175 offset:11584
	ds_read_b128 v[92:95], v123 offset:43264
	v_pk_mul_f32 v[106:107], v[64:65], v[44:45] op_sel_hi:[1,0]
	v_pk_mul_f32 v[108:109], v[64:65], v[56:57] op_sel_hi:[1,0]
	v_pk_fma_f32 v[106:107], v[66:67], v[44:45], v[106:107] op_sel:[0,1,0]
	v_pk_fma_f32 v[108:109], v[66:67], v[56:57], v[108:109] op_sel:[0,1,0]
	v_pk_fma_f32 v[106:107], v[68:69], v[46:47], v[106:107] op_sel_hi:[1,0,1]
	v_pk_fma_f32 v[108:109], v[68:69], v[58:59], v[108:109] op_sel_hi:[1,0,1]
	v_pk_fma_f32 v[106:107], v[70:71], v[46:47], v[106:107] op_sel:[0,1,0]
	v_pk_fma_f32 v[108:109], v[70:71], v[58:59], v[108:109] op_sel:[0,1,0]
	v_pk_mul_f32 v[110:111], v[64:65], v[40:41] op_sel_hi:[1,0]
	v_add_f32_dpp v106, v106, v106 quad_perm:[1,0,3,2] row_mask:0xf bank_mask:0xf bound_ctrl:1
	v_add_f32_dpp v107, v107, v107 quad_perm:[1,0,3,2] row_mask:0xf bank_mask:0xf bound_ctrl:1
	v_pk_fma_f32 v[108:109], v[62:63], v[176:177], v[108:109]
	v_pk_mul_f32 v[112:113], v[66:67], v[40:41] op_sel:[0,1]
	v_add_f32_dpp v106, v106, v106 quad_perm:[2,3,0,1] row_mask:0xf bank_mask:0xf bound_ctrl:1
	v_add_f32_dpp v107, v107, v107 quad_perm:[2,3,0,1] row_mask:0xf bank_mask:0xf bound_ctrl:1
	v_add_f32_dpp v148, v108, v108 row_half_mirror row_mask:0xf bank_mask:0xf bound_ctrl:1
	v_add_f32_dpp v148, v109, v109 row_half_mirror row_mask:0xf bank_mask:0xa
	v_add_f32_dpp v106, v106, v106 row_half_mirror row_mask:0xf bank_mask:0xf bound_ctrl:1
	v_add_f32_dpp v107, v107, v107 row_half_mirror row_mask:0xf bank_mask:0xf bound_ctrl:1
	v_pk_mul_f32 v[144:145], v[68:69], v[42:43] op_sel_hi:[1,0]
	v_pk_mul_f32 v[146:147], v[70:71], v[42:43] op_sel:[0,1]
	v_add_f32_dpp v106, v106, v106 row_mirror row_mask:0xf bank_mask:0xf bound_ctrl:1
	v_add_f32_dpp v107, v107, v107 row_mirror row_mask:0xf bank_mask:0xf bound_ctrl:1
	v_pk_fma_f32 v[110:111], v[60:61], v[52:53], v[110:111] op_sel_hi:[1,0,1]
	v_pk_fma_f32 v[112:113], v[60:61], v[52:53], v[112:113] op_sel:[0,1,0]
	v_pk_fma_f32 v[144:145], v[60:61], v[54:55], v[144:145] op_sel_hi:[1,0,1]
	v_pk_fma_f32 v[146:147], v[60:61], v[54:55], v[146:147] op_sel:[0,1,0]
	v_pk_fma_f32 v[64:65], v[106:107], v[48:49], v[110:111] op_sel_hi:[1,0,1]
	v_pk_fma_f32 v[66:67], v[106:107], v[48:49], v[112:113] op_sel:[0,1,0]
	v_pk_fma_f32 v[68:69], v[106:107], v[50:51], v[144:145] op_sel_hi:[1,0,1]
	v_pk_fma_f32 v[70:71], v[106:107], v[50:51], v[146:147] op_sel:[0,1,0]
	s_waitcnt lgkmcnt(0)
	ds_read_b128 v[40:43], v175 offset:12800
	ds_read_b128 v[44:47], v175 offset:12816
	ds_read_b128 v[48:51], v175 offset:12832
	ds_read_b128 v[52:55], v175 offset:12848
	ds_read_b128 v[56:59], v175 offset:12864
	ds_read_b128 v[60:63], v123 offset:43520
	v_pk_mul_f32 v[106:107], v[64:65], v[76:77] op_sel_hi:[1,0]
	v_pk_mul_f32 v[108:109], v[64:65], v[88:89] op_sel_hi:[1,0]
	v_pk_fma_f32 v[106:107], v[66:67], v[76:77], v[106:107] op_sel:[0,1,0]
	v_pk_fma_f32 v[108:109], v[66:67], v[88:89], v[108:109] op_sel:[0,1,0]
	v_pk_fma_f32 v[106:107], v[68:69], v[78:79], v[106:107] op_sel_hi:[1,0,1]
	v_pk_fma_f32 v[108:109], v[68:69], v[90:91], v[108:109] op_sel_hi:[1,0,1]
	v_pk_fma_f32 v[106:107], v[70:71], v[78:79], v[106:107] op_sel:[0,1,0]
	v_pk_fma_f32 v[108:109], v[70:71], v[90:91], v[108:109] op_sel:[0,1,0]
	v_pk_mul_f32 v[110:111], v[64:65], v[72:73] op_sel_hi:[1,0]
	v_add_f32_dpp v106, v106, v106 quad_perm:[1,0,3,2] row_mask:0xf bank_mask:0xf bound_ctrl:1
	v_add_f32_dpp v107, v107, v107 quad_perm:[1,0,3,2] row_mask:0xf bank_mask:0xf bound_ctrl:1
	v_pk_fma_f32 v[108:109], v[94:95], v[176:177], v[108:109]
	v_pk_mul_f32 v[112:113], v[66:67], v[72:73] op_sel:[0,1]
	v_add_f32_dpp v106, v106, v106 quad_perm:[2,3,0,1] row_mask:0xf bank_mask:0xf bound_ctrl:1
	v_add_f32_dpp v107, v107, v107 quad_perm:[2,3,0,1] row_mask:0xf bank_mask:0xf bound_ctrl:1
	v_add_f32_dpp v149, v108, v108 row_half_mirror row_mask:0xf bank_mask:0xf bound_ctrl:1
	v_add_f32_dpp v149, v109, v109 row_half_mirror row_mask:0xf bank_mask:0xa
	v_add_f32_dpp v106, v106, v106 row_half_mirror row_mask:0xf bank_mask:0xf bound_ctrl:1
	v_add_f32_dpp v107, v107, v107 row_half_mirror row_mask:0xf bank_mask:0xf bound_ctrl:1
	v_pk_mul_f32 v[144:145], v[68:69], v[74:75] op_sel_hi:[1,0]
	v_pk_mul_f32 v[146:147], v[70:71], v[74:75] op_sel:[0,1]
	v_add_f32_dpp v150, v148, v148 row_ror:8 row_mask:0xf bank_mask:0xf bound_ctrl:1
	v_add_f32_dpp v150, v149, v149 row_ror:8 row_mask:0xf bank_mask:0xc
	v_add_f32_dpp v106, v106, v106 row_mirror row_mask:0xf bank_mask:0xf bound_ctrl:1
	v_add_f32_dpp v107, v107, v107 row_mirror row_mask:0xf bank_mask:0xf bound_ctrl:1
	v_pk_fma_f32 v[110:111], v[92:93], v[84:85], v[110:111] op_sel_hi:[1,0,1]
	v_pk_fma_f32 v[112:113], v[92:93], v[84:85], v[112:113] op_sel:[0,1,0]
	v_pk_fma_f32 v[144:145], v[92:93], v[86:87], v[144:145] op_sel_hi:[1,0,1]
	v_pk_fma_f32 v[146:147], v[92:93], v[86:87], v[146:147] op_sel:[0,1,0]
	v_add_f32_dpp v150, v150, v150 quad_perm:[1,0,3,2] row_mask:0xf bank_mask:0xf bound_ctrl:1
	v_pk_fma_f32 v[64:65], v[106:107], v[80:81], v[110:111] op_sel_hi:[1,0,1]
	v_pk_fma_f32 v[66:67], v[106:107], v[80:81], v[112:113] op_sel:[0,1,0]
	v_add_f32_dpp v150, v150, v150 quad_perm:[2,3,0,1] row_mask:0xf bank_mask:0xf bound_ctrl:1
	v_pk_fma_f32 v[68:69], v[106:107], v[82:83], v[144:145] op_sel_hi:[1,0,1]
	v_pk_fma_f32 v[70:71], v[106:107], v[82:83], v[146:147] op_sel:[0,1,0]
	ds_write_b32 v178, v150 offset:1024
	s_waitcnt lgkmcnt(1)
; #define SC_GET(X, t) do { const float* p = rec + (t) * 320; w##X = *(const f32x4*)p; a##X = *(const f32x4*)(p + 4); b##X = *(const f32x4*)(p + 8); k##X = *(const f32x4*)(p + 12); q##X = *(const f32x4*)(p + 16); \
;                 v##X = *(const f32x4*)(VVa + (t) * 64); } while (0)
; DI void scan_phase(unsigned char* lds, const Ctx& a, const Op& d, const int variant) {
;     ...
;                 SC_GET(A, 0);
; #pragma unroll 2
;                 for (int t = 0; t < SC_T; t += 2) {
;                     SC_GET(B, t + 1);
;                     SC_STEP(A, t);
;                     if (t + 2 < SC_T) SC_GET(A, t + 2);
;                     SC_STEP(B, t + 1);
;                 }
	ds_read_b128 v[72:75], v175 offset:14080
	ds_read_b128 v[76:79], v175 offset:14096
	ds_read_b128 v[80:83], v175 offset:14112
	ds_read_b128 v[84:87], v175 offset:14128
	ds_read_b128 v[88:91], v175 offset:14144
	ds_read_b128 v[92:95], v123 offset:43776
	v_pk_mul_f32 v[106:107], v[64:65], v[44:45] op_sel_hi:[1,0]
	v_pk_mul_f32 v[108:109], v[64:65], v[56:57] op_sel_hi:[1,0]
	v_pk_fma_f32 v[106:107], v[66:67], v[44:45], v[106:107] op_sel:[0,1,0]
	v_pk_fma_f32 v[108:109], v[66:67], v[56:57], v[108:109] op_sel:[0,1,0]
	v_pk_fma_f32 v[106:107], v[68:69], v[46:47], v[106:107] op_sel_hi:[1,0,1]
	v_pk_fma_f32 v[108:109], v[68:69], v[58:59], v[108:109] op_sel_hi:[1,0,1]
	v_pk_fma_f32 v[106:107], v[70:71], v[46:47], v[106:107] op_sel:[0,1,0]
	v_pk_fma_f32 v[108:109], v[70:71], v[58:59], v[108:109] op_sel:[0,1,0]
	v_pk_mul_f32 v[110:111], v[64:65], v[40:41] op_sel_hi:[1,0]
	v_add_f32_dpp v106, v106, v106 quad_perm:[1,0,3,2] row_mask:0xf bank_mask:0xf bound_ctrl:1
	v_add_f32_dpp v107, v107, v107 quad_perm:[1,0,3,2] row_mask:0xf bank_mask:0xf bound_ctrl:1
	v_pk_fma_f32 v[108:109], v[62:63], v[176:177], v[108:109]
	v_pk_mul_f32 v[112:113], v[66:67], v[40:41] op_sel:[0,1]
	v_add_f32_dpp v106, v106, v106 quad_perm:[2,3,0,1] row_mask:0xf bank_mask:0xf bound_ctrl:1
	v_add_f32_dpp v107, v107, v107 quad_perm:[2,3,0,1] row_mask:0xf bank_mask:0xf bound_ctrl:1
	v_add_f32_dpp v148, v108, v108 row_half_mirror row_mask:0xf bank_mask:0xf bound_ctrl:1
	v_add_f32_dpp v148, v109, v109 row_half_mirror row_mask:0xf bank_mask:0xa
	v_add_f32_dpp v106, v106, v106 row_half_mirror row_mask:0xf bank_mask:0xf bound_ctrl:1
	v_add_f32_dpp v107, v107, v107 row_half_mirror row_mask:0xf bank_mask:0xf bound_ctrl:1
	v_pk_mul_f32 v[144:145], v[68:69], v[42:43] op_sel_hi:[1,0]
	v_pk_mul_f32 v[146:147], v[70:71], v[42:43] op_sel:[0,1]
	v_add_f32_dpp v106, v106, v106 row_mirror row_mask:0xf bank_mask:0xf bound_ctrl:1
	v_add_f32_dpp v107, v107, v107 row_mirror row_mask:0xf bank_mask:0xf bound_ctrl:1
	v_pk_fma_f32 v[110:111], v[60:61], v[52:53], v[110:111] op_sel_hi:[1,0,1]
	v_pk_fma_f32 v[112:113], v[60:61], v[52:53], v[112:113] op_sel:[0,1,0]
	v_pk_fma_f32 v[144:145], v[60:61], v[54:55], v[144:145] op_sel_hi:[1,0,1]
	v_pk_fma_f32 v[146:147], v[60:61], v[54:55], v[146:147] op_sel:[0,1,0]
	v_pk_fma_f32 v[64:65], v[106:107], v[48:49], v[110:111] op_sel_hi:[1,0,1]
	v_pk_fma_f32 v[66:67], v[106:107], v[48:49], v[112:113] op_sel:[0,1,0]
	v_pk_fma_f32 v[68:69], v[106:107], v[50:51], v[144:145] op_sel_hi:[1,0,1]
	v_pk_fma_f32 v[70:71], v[106:107], v[50:51], v[146:147] op_sel:[0,1,0]
	s_waitcnt lgkmcnt(0)
	ds_read_b128 v[40:43], v175 offset:15360
	ds_read_b128 v[44:47], v175 offset:15376
	ds_read_b128 v[48:51], v175 offset:15392
	ds_read_b128 v[52:55], v175 offset:15408
	ds_read_b128 v[56:59], v175 offset:15424
	ds_read_b128 v[60:63], v123 offset:44032
	v_pk_mul_f32 v[106:107], v[64:65], v[76:77] op_sel_hi:[1,0]
	v_pk_mul_f32 v[108:109], v[64:65], v[88:89] op_sel_hi:[1,0]
	v_pk_fma_f32 v[106:107], v[66:67], v[76:77], v[106:107] op_sel:[0,1,0]
	v_pk_fma_f32 v[108:109], v[66:67], v[88:89], v[108:109] op_sel:[0,1,0]
	v_pk_fma_f32 v[106:107], v[68:69], v[78:79], v[106:107] op_sel_hi:[1,0,1]
	v_pk_fma_f32 v[108:109], v[68:69], v[90:91], v[108:109] op_sel_hi:[1,0,1]
	v_pk_fma_f32 v[106:107], v[70:71], v[78:79], v[106:107] op_sel:[0,1,0]
	v_pk_fma_f32 v[108:109], v[70:71], v[90:91], v[108:109] op_sel:[0,1,0]
	v_pk_mul_f32 v[110:111], v[64:65], v[72:73] op_sel_hi:[1,0]
	v_add_f32_dpp v106, v106, v106 quad_perm:[1,0,3,2] row_mask:0xf bank_mask:0xf bound_ctrl:1
	v_add_f32_dpp v107, v107, v107 quad_perm:[1,0,3,2] row_mask:0xf bank_mask:0xf bound_ctrl:1
	v_pk_fma_f32 v[108:109], v[94:95], v[176:177], v[108:109]
	v_pk_mul_f32 v[112:113], v[66:67], v[72:73] op_sel:[0,1]
	v_add_f32_dpp v106, v106, v106 quad_perm:[2,3,0,1] row_mask:0xf bank_mask:0xf bound_ctrl:1
	v_add_f32_dpp v107, v107, v107 quad_perm:[2,3,0,1] row_mask:0xf bank_mask:0xf bound_ctrl:1
	v_add_f32_dpp v149, v108, v108 row_half_mirror row_mask:0xf bank_mask:0xf bound_ctrl:1
	v_add_f32_dpp v149, v109, v109 row_half_mirror row_mask:0xf bank_mask:0xa
	v_add_f32_dpp v106, v106, v106 row_half_mirror row_mask:0xf bank_mask:0xf bound_ctrl:1
	v_add_f32_dpp v107, v107, v107 row_half_mirror row_mask:0xf bank_mask:0xf bound_ctrl:1
	v_pk_mul_f32 v[144:145], v[68:69], v[74:75] op_sel_hi:[1,0]
	v_pk_mul_f32 v[146:147], v[70:71], v[74:75] op_sel:[0,1]
	v_add_f32_dpp v150, v148, v148 row_ror:8 row_mask:0xf bank_mask:0xf bound_ctrl:1
	v_add_f32_dpp v150, v149, v149 row_ror:8 row_mask:0xf bank_mask:0xc
	v_add_f32_dpp v106, v106, v106 row_mirror row_mask:0xf bank_mask:0xf bound_ctrl:1
	v_add_f32_dpp v107, v107, v107 row_mirror row_mask:0xf bank_mask:0xf bound_ctrl:1
	v_pk_fma_f32 v[110:111], v[92:93], v[84:85], v[110:111] op_sel_hi:[1,0,1]
	v_pk_fma_f32 v[112:113], v[92:93], v[84:85], v[112:113] op_sel:[0,1,0]
	v_pk_fma_f32 v[144:145], v[92:93], v[86:87], v[144:145] op_sel_hi:[1,0,1]
	v_pk_fma_f32 v[146:147], v[92:93], v[86:87], v[146:147] op_sel:[0,1,0]
	v_add_f32_dpp v150, v150, v150 quad_perm:[1,0,3,2] row_mask:0xf bank_mask:0xf bound_ctrl:1
	v_pk_fma_f32 v[64:65], v[106:107], v[80:81], v[110:111] op_sel_hi:[1,0,1]
	v_pk_fma_f32 v[66:67], v[106:107], v[80:81], v[112:113] op_sel:[0,1,0]
	v_add_f32_dpp v150, v150, v150 quad_perm:[2,3,0,1] row_mask:0xf bank_mask:0xf bound_ctrl:1
	v_pk_fma_f32 v[68:69], v[106:107], v[82:83], v[144:145] op_sel_hi:[1,0,1]
	v_pk_fma_f32 v[70:71], v[106:107], v[82:83], v[146:147] op_sel:[0,1,0]
	ds_write_b32 v178, v150 offset:1280
	s_waitcnt lgkmcnt(1)
; #define SC_GET(X, t) do { const float* p = rec + (t) * 320; w##X = *(const f32x4*)p; a##X = *(const f32x4*)(p + 4); b##X = *(const f32x4*)(p + 8); k##X = *(const f32x4*)(p + 12); q##X = *(const f32x4*)(p + 16); \
;                 v##X = *(const f32x4*)(VVa + (t) * 64); } while (0)
; DI void scan_phase(unsigned char* lds, const Ctx& a, const Op& d, const int variant) {
;     ...
;                 SC_GET(A, 0);
; #pragma unroll 2
;                 for (int t = 0; t < SC_T; t += 2) {
;                     SC_GET(B, t + 1);
;                     SC_STEP(A, t);
;                     if (t + 2 < SC_T) SC_GET(A, t + 2);
;                     SC_STEP(B, t + 1);
;                 }
	ds_read_b128 v[72:75], v175 offset:16640
	ds_read_b128 v[76:79], v175 offset:16656
	ds_read_b128 v[80:83], v175 offset:16672
	ds_read_b128 v[84:87], v175 offset:16688
	ds_read_b128 v[88:91], v175 offset:16704
	ds_read_b128 v[92:95], v123 offset:44288
	v_pk_mul_f32 v[106:107], v[64:65], v[44:45] op_sel_hi:[1,0]
	v_pk_mul_f32 v[108:109], v[64:65], v[56:57] op_sel_hi:[1,0]
	v_pk_fma_f32 v[106:107], v[66:67], v[44:45], v[106:107] op_sel:[0,1,0]
	v_pk_fma_f32 v[108:109], v[66:67], v[56:57], v[108:109] op_sel:[0,1,0]
	v_pk_fma_f32 v[106:107], v[68:69], v[46:47], v[106:107] op_sel_hi:[1,0,1]
	v_pk_fma_f32 v[108:109], v[68:69], v[58:59], v[108:109] op_sel_hi:[1,0,1]
	v_pk_fma_f32 v[106:107], v[70:71], v[46:47], v[106:107] op_sel:[0,1,0]
	v_pk_fma_f32 v[108:109], v[70:71], v[58:59], v[108:109] op_sel:[0,1,0]
	v_pk_mul_f32 v[110:111], v[64:65], v[40:41] op_sel_hi:[1,0]
	v_add_f32_dpp v106, v106, v106 quad_perm:[1,0,3,2] row_mask:0xf bank_mask:0xf bound_ctrl:1
	v_add_f32_dpp v107, v107, v107 quad_perm:[1,0,3,2] row_mask:0xf bank_mask:0xf bound_ctrl:1
	v_pk_fma_f32 v[108:109], v[62:63], v[176:177], v[108:109]
	v_pk_mul_f32 v[112:113], v[66:67], v[40:41] op_sel:[0,1]
	v_add_f32_dpp v106, v106, v106 quad_perm:[2,3,0,1] row_mask:0xf bank_mask:0xf bound_ctrl:1
	v_add_f32_dpp v107, v107, v107 quad_perm:[2,3,0,1] row_mask:0xf bank_mask:0xf bound_ctrl:1
	v_add_f32_dpp v148, v108, v108 row_half_mirror row_mask:0xf bank_mask:0xf bound_ctrl:1
	v_add_f32_dpp v148, v109, v109 row_half_mirror row_mask:0xf bank_mask:0xa
	v_add_f32_dpp v106, v106, v106 row_half_mirror row_mask:0xf bank_mask:0xf bound_ctrl:1
	v_add_f32_dpp v107, v107, v107 row_half_mirror row_mask:0xf bank_mask:0xf bound_ctrl:1
	v_pk_mul_f32 v[144:145], v[68:69], v[42:43] op_sel_hi:[1,0]
	v_pk_mul_f32 v[146:147], v[70:71], v[42:43] op_sel:[0,1]
	v_add_f32_dpp v106, v106, v106 row_mirror row_mask:0xf bank_mask:0xf bound_ctrl:1
	v_add_f32_dpp v107, v107, v107 row_mirror row_mask:0xf bank_mask:0xf bound_ctrl:1
	v_pk_fma_f32 v[110:111], v[60:61], v[52:53], v[110:111] op_sel_hi:[1,0,1]
	v_pk_fma_f32 v[112:113], v[60:61], v[52:53], v[112:113] op_sel:[0,1,0]
	v_pk_fma_f32 v[144:145], v[60:61], v[54:55], v[144:145] op_sel_hi:[1,0,1]
	v_pk_fma_f32 v[146:147], v[60:61], v[54:55], v[146:147] op_sel:[0,1,0]
	v_pk_fma_f32 v[64:65], v[106:107], v[48:49], v[110:111] op_sel_hi:[1,0,1]
	v_pk_fma_f32 v[66:67], v[106:107], v[48:49], v[112:113] op_sel:[0,1,0]
	v_pk_fma_f32 v[68:69], v[106:107], v[50:51], v[144:145] op_sel_hi:[1,0,1]
	v_pk_fma_f32 v[70:71], v[106:107], v[50:51], v[146:147] op_sel:[0,1,0]
	s_waitcnt lgkmcnt(0)
	ds_read_b128 v[40:43], v175 offset:17920
	ds_read_b128 v[44:47], v175 offset:17936
	ds_read_b128 v[48:51], v175 offset:17952
	ds_read_b128 v[52:55], v175 offset:17968
	ds_read_b128 v[56:59], v175 offset:17984
	ds_read_b128 v[60:63], v123 offset:44544
	v_pk_mul_f32 v[106:107], v[64:65], v[76:77] op_sel_hi:[1,0]
	v_pk_mul_f32 v[108:109], v[64:65], v[88:89] op_sel_hi:[1,0]
	v_pk_fma_f32 v[106:107], v[66:67], v[76:77], v[106:107] op_sel:[0,1,0]
	v_pk_fma_f32 v[108:109], v[66:67], v[88:89], v[108:109] op_sel:[0,1,0]
	v_pk_fma_f32 v[106:107], v[68:69], v[78:79], v[106:107] op_sel_hi:[1,0,1]
	v_pk_fma_f32 v[108:109], v[68:69], v[90:91], v[108:109] op_sel_hi:[1,0,1]
	v_pk_fma_f32 v[106:107], v[70:71], v[78:79], v[106:107] op_sel:[0,1,0]
	v_pk_fma_f32 v[108:109], v[70:71], v[90:91], v[108:109] op_sel:[0,1,0]
	v_pk_mul_f32 v[110:111], v[64:65], v[72:73] op_sel_hi:[1,0]
	v_add_f32_dpp v106, v106, v106 quad_perm:[1,0,3,2] row_mask:0xf bank_mask:0xf bound_ctrl:1
	v_add_f32_dpp v107, v107, v107 quad_perm:[1,0,3,2] row_mask:0xf bank_mask:0xf bound_ctrl:1
	v_pk_fma_f32 v[108:109], v[94:95], v[176:177], v[108:109]
	v_pk_mul_f32 v[112:113], v[66:67], v[72:73] op_sel:[0,1]
	v_add_f32_dpp v106, v106, v106 quad_perm:[2,3,0,1] row_mask:0xf bank_mask:0xf bound_ctrl:1
	v_add_f32_dpp v107, v107, v107 quad_perm:[2,3,0,1] row_mask:0xf bank_mask:0xf bound_ctrl:1
	v_add_f32_dpp v149, v108, v108 row_half_mirror row_mask:0xf bank_mask:0xf bound_ctrl:1
	v_add_f32_dpp v149, v109, v109 row_half_mirror row_mask:0xf bank_mask:0xa
	v_add_f32_dpp v106, v106, v106 row_half_mirror row_mask:0xf bank_mask:0xf bound_ctrl:1
	v_add_f32_dpp v107, v107, v107 row_half_mirror row_mask:0xf bank_mask:0xf bound_ctrl:1
	v_pk_mul_f32 v[144:145], v[68:69], v[74:75] op_sel_hi:[1,0]
	v_pk_mul_f32 v[146:147], v[70:71], v[74:75] op_sel:[0,1]
	v_add_f32_dpp v150, v148, v148 row_ror:8 row_mask:0xf bank_mask:0xf bound_ctrl:1
	v_add_f32_dpp v150, v149, v149 row_ror:8 row_mask:0xf bank_mask:0xc
	v_add_f32_dpp v106, v106, v106 row_mirror row_mask:0xf bank_mask:0xf bound_ctrl:1
	v_add_f32_dpp v107, v107, v107 row_mirror row_mask:0xf bank_mask:0xf bound_ctrl:1
	v_pk_fma_f32 v[110:111], v[92:93], v[84:85], v[110:111] op_sel_hi:[1,0,1]
	v_pk_fma_f32 v[112:113], v[92:93], v[84:85], v[112:113] op_sel:[0,1,0]
	v_pk_fma_f32 v[144:145], v[92:93], v[86:87], v[144:145] op_sel_hi:[1,0,1]
	v_pk_fma_f32 v[146:147], v[92:93], v[86:87], v[146:147] op_sel:[0,1,0]
	v_add_f32_dpp v150, v150, v150 quad_perm:[1,0,3,2] row_mask:0xf bank_mask:0xf bound_ctrl:1
	v_pk_fma_f32 v[64:65], v[106:107], v[80:81], v[110:111] op_sel_hi:[1,0,1]
	v_pk_fma_f32 v[66:67], v[106:107], v[80:81], v[112:113] op_sel:[0,1,0]
	v_add_f32_dpp v150, v150, v150 quad_perm:[2,3,0,1] row_mask:0xf bank_mask:0xf bound_ctrl:1
	v_pk_fma_f32 v[68:69], v[106:107], v[82:83], v[144:145] op_sel_hi:[1,0,1]
	v_pk_fma_f32 v[70:71], v[106:107], v[82:83], v[146:147] op_sel:[0,1,0]
	ds_write_b32 v178, v150 offset:1536
	s_waitcnt lgkmcnt(1)
; #define SC_GET(X, t) do { const float* p = rec + (t) * 320; w##X = *(const f32x4*)p; a##X = *(const f32x4*)(p + 4); b##X = *(const f32x4*)(p + 8); k##X = *(const f32x4*)(p + 12); q##X = *(const f32x4*)(p + 16); \
;                 v##X = *(const f32x4*)(VVa + (t) * 64); } while (0)
; DI void scan_phase(unsigned char* lds, const Ctx& a, const Op& d, const int variant) {
;     ...
;                 SC_GET(A, 0);
; #pragma unroll 2
;                 for (int t = 0; t < SC_T; t += 2) {
;                     SC_GET(B, t + 1);
;                     SC_STEP(A, t);
;                     if (t + 2 < SC_T) SC_GET(A, t + 2);
;                     SC_STEP(B, t + 1);
;                 }
	ds_read_b128 v[72:75], v175 offset:19200
	ds_read_b128 v[76:79], v175 offset:19216
	ds_read_b128 v[80:83], v175 offset:19232
	ds_read_b128 v[84:87], v175 offset:19248
	ds_read_b128 v[88:91], v175 offset:19264
	ds_read_b128 v[92:95], v123 offset:44800
	v_pk_mul_f32 v[106:107], v[64:65], v[44:45] op_sel_hi:[1,0]
	v_pk_mul_f32 v[108:109], v[64:65], v[56:57] op_sel_hi:[1,0]
	v_pk_fma_f32 v[106:107], v[66:67], v[44:45], v[106:107] op_sel:[0,1,0]
	v_pk_fma_f32 v[108:109], v[66:67], v[56:57], v[108:109] op_sel:[0,1,0]
	v_pk_fma_f32 v[106:107], v[68:69], v[46:47], v[106:107] op_sel_hi:[1,0,1]
	v_pk_fma_f32 v[108:109], v[68:69], v[58:59], v[108:109] op_sel_hi:[1,0,1]
	v_pk_fma_f32 v[106:107], v[70:71], v[46:47], v[106:107] op_sel:[0,1,0]
	v_pk_fma_f32 v[108:109], v[70:71], v[58:59], v[108:109] op_sel:[0,1,0]
	v_pk_mul_f32 v[110:111], v[64:65], v[40:41] op_sel_hi:[1,0]
	v_add_f32_dpp v106, v106, v106 quad_perm:[1,0,3,2] row_mask:0xf bank_mask:0xf bound_ctrl:1
	v_add_f32_dpp v107, v107, v107 quad_perm:[1,0,3,2] row_mask:0xf bank_mask:0xf bound_ctrl:1
	v_pk_fma_f32 v[108:109], v[62:63], v[176:177], v[108:109]
	v_pk_mul_f32 v[112:113], v[66:67], v[40:41] op_sel:[0,1]
	v_add_f32_dpp v106, v106, v106 quad_perm:[2,3,0,1] row_mask:0xf bank_mask:0xf bound_ctrl:1
	v_add_f32_dpp v107, v107, v107 quad_perm:[2,3,0,1] row_mask:0xf bank_mask:0xf bound_ctrl:1
	v_add_f32_dpp v148, v108, v108 row_half_mirror row_mask:0xf bank_mask:0xf bound_ctrl:1
	v_add_f32_dpp v148, v109, v109 row_half_mirror row_mask:0xf bank_mask:0xa
	v_add_f32_dpp v106, v106, v106 row_half_mirror row_mask:0xf bank_mask:0xf bound_ctrl:1
	v_add_f32_dpp v107, v107, v107 row_half_mirror row_mask:0xf bank_mask:0xf bound_ctrl:1
	v_pk_mul_f32 v[144:145], v[68:69], v[42:43] op_sel_hi:[1,0]
	v_pk_mul_f32 v[146:147], v[70:71], v[42:43] op_sel:[0,1]
	v_add_f32_dpp v106, v106, v106 row_mirror row_mask:0xf bank_mask:0xf bound_ctrl:1
	v_add_f32_dpp v107, v107, v107 row_mirror row_mask:0xf bank_mask:0xf bound_ctrl:1
	v_pk_fma_f32 v[110:111], v[60:61], v[52:53], v[110:111] op_sel_hi:[1,0,1]
	v_pk_fma_f32 v[112:113], v[60:61], v[52:53], v[112:113] op_sel:[0,1,0]
	v_pk_fma_f32 v[144:145], v[60:61], v[54:55], v[144:145] op_sel_hi:[1,0,1]
	v_pk_fma_f32 v[146:147], v[60:61], v[54:55], v[146:147] op_sel:[0,1,0]
	v_pk_fma_f32 v[64:65], v[106:107], v[48:49], v[110:111] op_sel_hi:[1,0,1]
	v_pk_fma_f32 v[66:67], v[106:107], v[48:49], v[112:113] op_sel:[0,1,0]
	v_pk_fma_f32 v[68:69], v[106:107], v[50:51], v[144:145] op_sel_hi:[1,0,1]
	v_pk_fma_f32 v[70:71], v[106:107], v[50:51], v[146:147] op_sel:[0,1,0]
	s_waitcnt lgkmcnt(0)
	ds_read_b128 v[40:43], v175 offset:20480
	ds_read_b128 v[44:47], v175 offset:20496
	ds_read_b128 v[48:51], v175 offset:20512
	ds_read_b128 v[52:55], v175 offset:20528
	ds_read_b128 v[56:59], v175 offset:20544
	ds_read_b128 v[60:63], v123 offset:45056
	v_pk_mul_f32 v[106:107], v[64:65], v[76:77] op_sel_hi:[1,0]
	v_pk_mul_f32 v[108:109], v[64:65], v[88:89] op_sel_hi:[1,0]
	v_pk_fma_f32 v[106:107], v[66:67], v[76:77], v[106:107] op_sel:[0,1,0]
	v_pk_fma_f32 v[108:109], v[66:67], v[88:89], v[108:109] op_sel:[0,1,0]
	v_pk_fma_f32 v[106:107], v[68:69], v[78:79], v[106:107] op_sel_hi:[1,0,1]
	v_pk_fma_f32 v[108:109], v[68:69], v[90:91], v[108:109] op_sel_hi:[1,0,1]
	v_pk_fma_f32 v[106:107], v[70:71], v[78:79], v[106:107] op_sel:[0,1,0]
	v_pk_fma_f32 v[108:109], v[70:71], v[90:91], v[108:109] op_sel:[0,1,0]
	v_pk_mul_f32 v[110:111], v[64:65], v[72:73] op_sel_hi:[1,0]
	v_add_f32_dpp v106, v106, v106 quad_perm:[1,0,3,2] row_mask:0xf bank_mask:0xf bound_ctrl:1
	v_add_f32_dpp v107, v107, v107 quad_perm:[1,0,3,2] row_mask:0xf bank_mask:0xf bound_ctrl:1
	v_pk_fma_f32 v[108:109], v[94:95], v[176:177], v[108:109]
	v_pk_mul_f32 v[112:113], v[66:67], v[72:73] op_sel:[0,1]
	v_add_f32_dpp v106, v106, v106 quad_perm:[2,3,0,1] row_mask:0xf bank_mask:0xf bound_ctrl:1
	v_add_f32_dpp v107, v107, v107 quad_perm:[2,3,0,1] row_mask:0xf bank_mask:0xf bound_ctrl:1
	v_add_f32_dpp v149, v108, v108 row_half_mirror row_mask:0xf bank_mask:0xf bound_ctrl:1
	v_add_f32_dpp v149, v109, v109 row_half_mirror row_mask:0xf bank_mask:0xa
	v_add_f32_dpp v106, v106, v106 row_half_mirror row_mask:0xf bank_mask:0xf bound_ctrl:1
	v_add_f32_dpp v107, v107, v107 row_half_mirror row_mask:0xf bank_mask:0xf bound_ctrl:1
	v_pk_mul_f32 v[144:145], v[68:69], v[74:75] op_sel_hi:[1,0]
	v_pk_mul_f32 v[146:147], v[70:71], v[74:75] op_sel:[0,1]
	v_add_f32_dpp v150, v148, v148 row_ror:8 row_mask:0xf bank_mask:0xf bound_ctrl:1
	v_add_f32_dpp v150, v149, v149 row_ror:8 row_mask:0xf bank_mask:0xc
	v_add_f32_dpp v106, v106, v106 row_mirror row_mask:0xf bank_mask:0xf bound_ctrl:1
	v_add_f32_dpp v107, v107, v107 row_mirror row_mask:0xf bank_mask:0xf bound_ctrl:1
	v_pk_fma_f32 v[110:111], v[92:93], v[84:85], v[110:111] op_sel_hi:[1,0,1]
	v_pk_fma_f32 v[112:113], v[92:93], v[84:85], v[112:113] op_sel:[0,1,0]
	v_pk_fma_f32 v[144:145], v[92:93], v[86:87], v[144:145] op_sel_hi:[1,0,1]
	v_pk_fma_f32 v[146:147], v[92:93], v[86:87], v[146:147] op_sel:[0,1,0]
	v_add_f32_dpp v150, v150, v150 quad_perm:[1,0,3,2] row_mask:0xf bank_mask:0xf bound_ctrl:1
	v_pk_fma_f32 v[64:65], v[106:107], v[80:81], v[110:111] op_sel_hi:[1,0,1]
	v_pk_fma_f32 v[66:67], v[106:107], v[80:81], v[112:113] op_sel:[0,1,0]
	v_add_f32_dpp v150, v150, v150 quad_perm:[2,3,0,1] row_mask:0xf bank_mask:0xf bound_ctrl:1
	v_pk_fma_f32 v[68:69], v[106:107], v[82:83], v[144:145] op_sel_hi:[1,0,1]
	v_pk_fma_f32 v[70:71], v[106:107], v[82:83], v[146:147] op_sel:[0,1,0]
	ds_write_b32 v178, v150 offset:1792
	s_waitcnt lgkmcnt(1)
; #define SC_GET(X, t) do { const float* p = rec + (t) * 320; w##X = *(const f32x4*)p; a##X = *(const f32x4*)(p + 4); b##X = *(const f32x4*)(p + 8); k##X = *(const f32x4*)(p + 12); q##X = *(const f32x4*)(p + 16); \
;                 v##X = *(const f32x4*)(VVa + (t) * 64); } while (0)
; DI void scan_phase(unsigned char* lds, const Ctx& a, const Op& d, const int variant) {
;     ...
;                 SC_GET(A, 0);
; #pragma unroll 2
;                 for (int t = 0; t < SC_T; t += 2) {
;                     SC_GET(B, t + 1);
;                     SC_STEP(A, t);
;                     if (t + 2 < SC_T) SC_GET(A, t + 2);
;                     SC_STEP(B, t + 1);
;                 }
	ds_read_b128 v[72:75], v175 offset:21760
	ds_read_b128 v[76:79], v175 offset:21776
	ds_read_b128 v[80:83], v175 offset:21792
	ds_read_b128 v[84:87], v175 offset:21808
	ds_read_b128 v[88:91], v175 offset:21824
	ds_read_b128 v[92:95], v123 offset:45312
	v_pk_mul_f32 v[106:107], v[64:65], v[44:45] op_sel_hi:[1,0]
	v_pk_mul_f32 v[108:109], v[64:65], v[56:57] op_sel_hi:[1,0]
	v_pk_fma_f32 v[106:107], v[66:67], v[44:45], v[106:107] op_sel:[0,1,0]
	v_pk_fma_f32 v[108:109], v[66:67], v[56:57], v[108:109] op_sel:[0,1,0]
	v_pk_fma_f32 v[106:107], v[68:69], v[46:47], v[106:107] op_sel_hi:[1,0,1]
	v_pk_fma_f32 v[108:109], v[68:69], v[58:59], v[108:109] op_sel_hi:[1,0,1]
	v_pk_fma_f32 v[106:107], v[70:71], v[46:47], v[106:107] op_sel:[0,1,0]
	v_pk_fma_f32 v[108:109], v[70:71], v[58:59], v[108:109] op_sel:[0,1,0]
	v_pk_mul_f32 v[110:111], v[64:65], v[40:41] op_sel_hi:[1,0]
	v_add_f32_dpp v106, v106, v106 quad_perm:[1,0,3,2] row_mask:0xf bank_mask:0xf bound_ctrl:1
	v_add_f32_dpp v107, v107, v107 quad_perm:[1,0,3,2] row_mask:0xf bank_mask:0xf bound_ctrl:1
	v_pk_fma_f32 v[108:109], v[62:63], v[176:177], v[108:109]
	v_pk_mul_f32 v[112:113], v[66:67], v[40:41] op_sel:[0,1]
	v_add_f32_dpp v106, v106, v106 quad_perm:[2,3,0,1] row_mask:0xf bank_mask:0xf bound_ctrl:1
	v_add_f32_dpp v107, v107, v107 quad_perm:[2,3,0,1] row_mask:0xf bank_mask:0xf bound_ctrl:1
	v_add_f32_dpp v148, v108, v108 row_half_mirror row_mask:0xf bank_mask:0xf bound_ctrl:1
	v_add_f32_dpp v148, v109, v109 row_half_mirror row_mask:0xf bank_mask:0xa
	v_add_f32_dpp v106, v106, v106 row_half_mirror row_mask:0xf bank_mask:0xf bound_ctrl:1
	v_add_f32_dpp v107, v107, v107 row_half_mirror row_mask:0xf bank_mask:0xf bound_ctrl:1
	v_pk_mul_f32 v[144:145], v[68:69], v[42:43] op_sel_hi:[1,0]
	v_pk_mul_f32 v[146:147], v[70:71], v[42:43] op_sel:[0,1]
	v_add_f32_dpp v106, v106, v106 row_mirror row_mask:0xf bank_mask:0xf bound_ctrl:1
	v_add_f32_dpp v107, v107, v107 row_mirror row_mask:0xf bank_mask:0xf bound_ctrl:1
	v_pk_fma_f32 v[110:111], v[60:61], v[52:53], v[110:111] op_sel_hi:[1,0,1]
	v_pk_fma_f32 v[112:113], v[60:61], v[52:53], v[112:113] op_sel:[0,1,0]
	v_pk_fma_f32 v[144:145], v[60:61], v[54:55], v[144:145] op_sel_hi:[1,0,1]
	v_pk_fma_f32 v[146:147], v[60:61], v[54:55], v[146:147] op_sel:[0,1,0]
	v_pk_fma_f32 v[64:65], v[106:107], v[48:49], v[110:111] op_sel_hi:[1,0,1]
	v_pk_fma_f32 v[66:67], v[106:107], v[48:49], v[112:113] op_sel:[0,1,0]
	v_pk_fma_f32 v[68:69], v[106:107], v[50:51], v[144:145] op_sel_hi:[1,0,1]
	v_pk_fma_f32 v[70:71], v[106:107], v[50:51], v[146:147] op_sel:[0,1,0]
	s_waitcnt lgkmcnt(0)
	ds_read_b128 v[40:43], v175 offset:23040
	ds_read_b128 v[44:47], v175 offset:23056
	ds_read_b128 v[48:51], v175 offset:23072
	ds_read_b128 v[52:55], v175 offset:23088
	ds_read_b128 v[56:59], v175 offset:23104
	ds_read_b128 v[60:63], v123 offset:45568
	v_pk_mul_f32 v[106:107], v[64:65], v[76:77] op_sel_hi:[1,0]
	v_pk_mul_f32 v[108:109], v[64:65], v[88:89] op_sel_hi:[1,0]
	v_pk_fma_f32 v[106:107], v[66:67], v[76:77], v[106:107] op_sel:[0,1,0]
	v_pk_fma_f32 v[108:109], v[66:67], v[88:89], v[108:109] op_sel:[0,1,0]
	v_pk_fma_f32 v[106:107], v[68:69], v[78:79], v[106:107] op_sel_hi:[1,0,1]
	v_pk_fma_f32 v[108:109], v[68:69], v[90:91], v[108:109] op_sel_hi:[1,0,1]
	v_pk_fma_f32 v[106:107], v[70:71], v[78:79], v[106:107] op_sel:[0,1,0]
	v_pk_fma_f32 v[108:109], v[70:71], v[90:91], v[108:109] op_sel:[0,1,0]
	v_pk_mul_f32 v[110:111], v[64:65], v[72:73] op_sel_hi:[1,0]
	v_add_f32_dpp v106, v106, v106 quad_perm:[1,0,3,2] row_mask:0xf bank_mask:0xf bound_ctrl:1
	v_add_f32_dpp v107, v107, v107 quad_perm:[1,0,3,2] row_mask:0xf bank_mask:0xf bound_ctrl:1
	v_pk_fma_f32 v[108:109], v[94:95], v[176:177], v[108:109]
	v_pk_mul_f32 v[112:113], v[66:67], v[72:73] op_sel:[0,1]
	v_add_f32_dpp v106, v106, v106 quad_perm:[2,3,0,1] row_mask:0xf bank_mask:0xf bound_ctrl:1
	v_add_f32_dpp v107, v107, v107 quad_perm:[2,3,0,1] row_mask:0xf bank_mask:0xf bound_ctrl:1
	v_add_f32_dpp v149, v108, v108 row_half_mirror row_mask:0xf bank_mask:0xf bound_ctrl:1
	v_add_f32_dpp v149, v109, v109 row_half_mirror row_mask:0xf bank_mask:0xa
	v_add_f32_dpp v106, v106, v106 row_half_mirror row_mask:0xf bank_mask:0xf bound_ctrl:1
	v_add_f32_dpp v107, v107, v107 row_half_mirror row_mask:0xf bank_mask:0xf bound_ctrl:1
	v_pk_mul_f32 v[144:145], v[68:69], v[74:75] op_sel_hi:[1,0]
	v_pk_mul_f32 v[146:147], v[70:71], v[74:75] op_sel:[0,1]
	v_add_f32_dpp v150, v148, v148 row_ror:8 row_mask:0xf bank_mask:0xf bound_ctrl:1
	v_add_f32_dpp v150, v149, v149 row_ror:8 row_mask:0xf bank_mask:0xc
	v_add_f32_dpp v106, v106, v106 row_mirror row_mask:0xf bank_mask:0xf bound_ctrl:1
	v_add_f32_dpp v107, v107, v107 row_mirror row_mask:0xf bank_mask:0xf bound_ctrl:1
	v_pk_fma_f32 v[110:111], v[92:93], v[84:85], v[110:111] op_sel_hi:[1,0,1]
	v_pk_fma_f32 v[112:113], v[92:93], v[84:85], v[112:113] op_sel:[0,1,0]
	v_pk_fma_f32 v[144:145], v[92:93], v[86:87], v[144:145] op_sel_hi:[1,0,1]
	v_pk_fma_f32 v[146:147], v[92:93], v[86:87], v[146:147] op_sel:[0,1,0]
	v_add_f32_dpp v150, v150, v150 quad_perm:[1,0,3,2] row_mask:0xf bank_mask:0xf bound_ctrl:1
	v_pk_fma_f32 v[64:65], v[106:107], v[80:81], v[110:111] op_sel_hi:[1,0,1]
	v_pk_fma_f32 v[66:67], v[106:107], v[80:81], v[112:113] op_sel:[0,1,0]
	v_add_f32_dpp v150, v150, v150 quad_perm:[2,3,0,1] row_mask:0xf bank_mask:0xf bound_ctrl:1
	v_pk_fma_f32 v[68:69], v[106:107], v[82:83], v[144:145] op_sel_hi:[1,0,1]
	v_pk_fma_f32 v[70:71], v[106:107], v[82:83], v[146:147] op_sel:[0,1,0]
	ds_write_b32 v178, v150 offset:2048
	s_waitcnt lgkmcnt(1)
; #define SC_GET(X, t) do { const float* p = rec + (t) * 320; w##X = *(const f32x4*)p; a##X = *(const f32x4*)(p + 4); b##X = *(const f32x4*)(p + 8); k##X = *(const f32x4*)(p + 12); q##X = *(const f32x4*)(p + 16); \
;                 v##X = *(const f32x4*)(VVa + (t) * 64); } while (0)
; DI void scan_phase(unsigned char* lds, const Ctx& a, const Op& d, const int variant) {
;     ...
;                 SC_GET(A, 0);
; #pragma unroll 2
;                 for (int t = 0; t < SC_T; t += 2) {
;                     SC_GET(B, t + 1);
;                     SC_STEP(A, t);
;                     if (t + 2 < SC_T) SC_GET(A, t + 2);
;                     SC_STEP(B, t + 1);
;                 }
	ds_read_b128 v[72:75], v175 offset:24320
	ds_read_b128 v[76:79], v175 offset:24336
	ds_read_b128 v[80:83], v175 offset:24352
	ds_read_b128 v[84:87], v175 offset:24368
	ds_read_b128 v[88:91], v175 offset:24384
	ds_read_b128 v[92:95], v123 offset:45824
	v_pk_mul_f32 v[106:107], v[64:65], v[44:45] op_sel_hi:[1,0]
	v_pk_mul_f32 v[108:109], v[64:65], v[56:57] op_sel_hi:[1,0]
	v_pk_fma_f32 v[106:107], v[66:67], v[44:45], v[106:107] op_sel:[0,1,0]
	v_pk_fma_f32 v[108:109], v[66:67], v[56:57], v[108:109] op_sel:[0,1,0]
	v_pk_fma_f32 v[106:107], v[68:69], v[46:47], v[106:107] op_sel_hi:[1,0,1]
	v_pk_fma_f32 v[108:109], v[68:69], v[58:59], v[108:109] op_sel_hi:[1,0,1]
	v_pk_fma_f32 v[106:107], v[70:71], v[46:47], v[106:107] op_sel:[0,1,0]
	v_pk_fma_f32 v[108:109], v[70:71], v[58:59], v[108:109] op_sel:[0,1,0]
	v_pk_mul_f32 v[110:111], v[64:65], v[40:41] op_sel_hi:[1,0]
	v_add_f32_dpp v106, v106, v106 quad_perm:[1,0,3,2] row_mask:0xf bank_mask:0xf bound_ctrl:1
	v_add_f32_dpp v107, v107, v107 quad_perm:[1,0,3,2] row_mask:0xf bank_mask:0xf bound_ctrl:1
	v_pk_fma_f32 v[108:109], v[62:63], v[176:177], v[108:109]
	v_pk_mul_f32 v[112:113], v[66:67], v[40:41] op_sel:[0,1]
	v_add_f32_dpp v106, v106, v106 quad_perm:[2,3,0,1] row_mask:0xf bank_mask:0xf bound_ctrl:1
	v_add_f32_dpp v107, v107, v107 quad_perm:[2,3,0,1] row_mask:0xf bank_mask:0xf bound_ctrl:1
	v_add_f32_dpp v148, v108, v108 row_half_mirror row_mask:0xf bank_mask:0xf bound_ctrl:1
	v_add_f32_dpp v148, v109, v109 row_half_mirror row_mask:0xf bank_mask:0xa
	v_add_f32_dpp v106, v106, v106 row_half_mirror row_mask:0xf bank_mask:0xf bound_ctrl:1
	v_add_f32_dpp v107, v107, v107 row_half_mirror row_mask:0xf bank_mask:0xf bound_ctrl:1
	v_pk_mul_f32 v[144:145], v[68:69], v[42:43] op_sel_hi:[1,0]
	v_pk_mul_f32 v[146:147], v[70:71], v[42:43] op_sel:[0,1]
	v_add_f32_dpp v106, v106, v106 row_mirror row_mask:0xf bank_mask:0xf bound_ctrl:1
	v_add_f32_dpp v107, v107, v107 row_mirror row_mask:0xf bank_mask:0xf bound_ctrl:1
	v_pk_fma_f32 v[110:111], v[60:61], v[52:53], v[110:111] op_sel_hi:[1,0,1]
	v_pk_fma_f32 v[112:113], v[60:61], v[52:53], v[112:113] op_sel:[0,1,0]
	v_pk_fma_f32 v[144:145], v[60:61], v[54:55], v[144:145] op_sel_hi:[1,0,1]
	v_pk_fma_f32 v[146:147], v[60:61], v[54:55], v[146:147] op_sel:[0,1,0]
	v_pk_fma_f32 v[64:65], v[106:107], v[48:49], v[110:111] op_sel_hi:[1,0,1]
	v_pk_fma_f32 v[66:67], v[106:107], v[48:49], v[112:113] op_sel:[0,1,0]
	v_pk_fma_f32 v[68:69], v[106:107], v[50:51], v[144:145] op_sel_hi:[1,0,1]
	v_pk_fma_f32 v[70:71], v[106:107], v[50:51], v[146:147] op_sel:[0,1,0]
	s_waitcnt lgkmcnt(0)
	ds_read_b128 v[40:43], v175 offset:25600
	ds_read_b128 v[44:47], v175 offset:25616
	ds_read_b128 v[48:51], v175 offset:25632
	ds_read_b128 v[52:55], v175 offset:25648
	ds_read_b128 v[56:59], v175 offset:25664
	ds_read_b128 v[60:63], v123 offset:46080
	v_pk_mul_f32 v[106:107], v[64:65], v[76:77] op_sel_hi:[1,0]
	v_pk_mul_f32 v[108:109], v[64:65], v[88:89] op_sel_hi:[1,0]
	v_pk_fma_f32 v[106:107], v[66:67], v[76:77], v[106:107] op_sel:[0,1,0]
	v_pk_fma_f32 v[108:109], v[66:67], v[88:89], v[108:109] op_sel:[0,1,0]
	v_pk_fma_f32 v[106:107], v[68:69], v[78:79], v[106:107] op_sel_hi:[1,0,1]
	v_pk_fma_f32 v[108:109], v[68:69], v[90:91], v[108:109] op_sel_hi:[1,0,1]
	v_pk_fma_f32 v[106:107], v[70:71], v[78:79], v[106:107] op_sel:[0,1,0]
	v_pk_fma_f32 v[108:109], v[70:71], v[90:91], v[108:109] op_sel:[0,1,0]
	v_pk_mul_f32 v[110:111], v[64:65], v[72:73] op_sel_hi:[1,0]
	v_add_f32_dpp v106, v106, v106 quad_perm:[1,0,3,2] row_mask:0xf bank_mask:0xf bound_ctrl:1
	v_add_f32_dpp v107, v107, v107 quad_perm:[1,0,3,2] row_mask:0xf bank_mask:0xf bound_ctrl:1
	v_pk_fma_f32 v[108:109], v[94:95], v[176:177], v[108:109]
	v_pk_mul_f32 v[112:113], v[66:67], v[72:73] op_sel:[0,1]
	v_add_f32_dpp v106, v106, v106 quad_perm:[2,3,0,1] row_mask:0xf bank_mask:0xf bound_ctrl:1
	v_add_f32_dpp v107, v107, v107 quad_perm:[2,3,0,1] row_mask:0xf bank_mask:0xf bound_ctrl:1
	v_add_f32_dpp v149, v108, v108 row_half_mirror row_mask:0xf bank_mask:0xf bound_ctrl:1
	v_add_f32_dpp v149, v109, v109 row_half_mirror row_mask:0xf bank_mask:0xa
	v_add_f32_dpp v106, v106, v106 row_half_mirror row_mask:0xf bank_mask:0xf bound_ctrl:1
	v_add_f32_dpp v107, v107, v107 row_half_mirror row_mask:0xf bank_mask:0xf bound_ctrl:1
	v_pk_mul_f32 v[144:145], v[68:69], v[74:75] op_sel_hi:[1,0]
	v_pk_mul_f32 v[146:147], v[70:71], v[74:75] op_sel:[0,1]
	v_add_f32_dpp v150, v148, v148 row_ror:8 row_mask:0xf bank_mask:0xf bound_ctrl:1
	v_add_f32_dpp v150, v149, v149 row_ror:8 row_mask:0xf bank_mask:0xc
	v_add_f32_dpp v106, v106, v106 row_mirror row_mask:0xf bank_mask:0xf bound_ctrl:1
	v_add_f32_dpp v107, v107, v107 row_mirror row_mask:0xf bank_mask:0xf bound_ctrl:1
	v_pk_fma_f32 v[110:111], v[92:93], v[84:85], v[110:111] op_sel_hi:[1,0,1]
	v_pk_fma_f32 v[112:113], v[92:93], v[84:85], v[112:113] op_sel:[0,1,0]
	v_pk_fma_f32 v[144:145], v[92:93], v[86:87], v[144:145] op_sel_hi:[1,0,1]
	v_pk_fma_f32 v[146:147], v[92:93], v[86:87], v[146:147] op_sel:[0,1,0]
	v_add_f32_dpp v150, v150, v150 quad_perm:[1,0,3,2] row_mask:0xf bank_mask:0xf bound_ctrl:1
	v_pk_fma_f32 v[64:65], v[106:107], v[80:81], v[110:111] op_sel_hi:[1,0,1]
	v_pk_fma_f32 v[66:67], v[106:107], v[80:81], v[112:113] op_sel:[0,1,0]
	v_add_f32_dpp v150, v150, v150 quad_perm:[2,3,0,1] row_mask:0xf bank_mask:0xf bound_ctrl:1
	v_pk_fma_f32 v[68:69], v[106:107], v[82:83], v[144:145] op_sel_hi:[1,0,1]
	v_pk_fma_f32 v[70:71], v[106:107], v[82:83], v[146:147] op_sel:[0,1,0]
	ds_write_b32 v178, v150 offset:2304
	s_waitcnt lgkmcnt(1)
; #define SC_GET(X, t) do { const float* p = rec + (t) * 320; w##X = *(const f32x4*)p; a##X = *(const f32x4*)(p + 4); b##X = *(const f32x4*)(p + 8); k##X = *(const f32x4*)(p + 12); q##X = *(const f32x4*)(p + 16); \
;                 v##X = *(const f32x4*)(VVa + (t) * 64); } while (0)
; DI void scan_phase(unsigned char* lds, const Ctx& a, const Op& d, const int variant) {
;     ...
;                 SC_GET(A, 0);
; #pragma unroll 2
;                 for (int t = 0; t < SC_T; t += 2) {
;                     SC_GET(B, t + 1);
;                     SC_STEP(A, t);
;                     if (t + 2 < SC_T) SC_GET(A, t + 2);
;                     SC_STEP(B, t + 1);
;                 }
	ds_read_b128 v[72:75], v175 offset:26880
	ds_read_b128 v[76:79], v175 offset:26896
	ds_read_b128 v[80:83], v175 offset:26912
	ds_read_b128 v[84:87], v175 offset:26928
	ds_read_b128 v[88:91], v175 offset:26944
	ds_read_b128 v[92:95], v123 offset:46336
	v_pk_mul_f32 v[106:107], v[64:65], v[44:45] op_sel_hi:[1,0]
	v_pk_mul_f32 v[108:109], v[64:65], v[56:57] op_sel_hi:[1,0]
	v_pk_fma_f32 v[106:107], v[66:67], v[44:45], v[106:107] op_sel:[0,1,0]
	v_pk_fma_f32 v[108:109], v[66:67], v[56:57], v[108:109] op_sel:[0,1,0]
	v_pk_fma_f32 v[106:107], v[68:69], v[46:47], v[106:107] op_sel_hi:[1,0,1]
	v_pk_fma_f32 v[108:109], v[68:69], v[58:59], v[108:109] op_sel_hi:[1,0,1]
	v_pk_fma_f32 v[106:107], v[70:71], v[46:47], v[106:107] op_sel:[0,1,0]
	v_pk_fma_f32 v[108:109], v[70:71], v[58:59], v[108:109] op_sel:[0,1,0]
	v_pk_mul_f32 v[110:111], v[64:65], v[40:41] op_sel_hi:[1,0]
	v_add_f32_dpp v106, v106, v106 quad_perm:[1,0,3,2] row_mask:0xf bank_mask:0xf bound_ctrl:1
	v_add_f32_dpp v107, v107, v107 quad_perm:[1,0,3,2] row_mask:0xf bank_mask:0xf bound_ctrl:1
	v_pk_fma_f32 v[108:109], v[62:63], v[176:177], v[108:109]
	v_pk_mul_f32 v[112:113], v[66:67], v[40:41] op_sel:[0,1]
	v_add_f32_dpp v106, v106, v106 quad_perm:[2,3,0,1] row_mask:0xf bank_mask:0xf bound_ctrl:1
	v_add_f32_dpp v107, v107, v107 quad_perm:[2,3,0,1] row_mask:0xf bank_mask:0xf bound_ctrl:1
	v_add_f32_dpp v148, v108, v108 row_half_mirror row_mask:0xf bank_mask:0xf bound_ctrl:1
	v_add_f32_dpp v148, v109, v109 row_half_mirror row_mask:0xf bank_mask:0xa
	v_add_f32_dpp v106, v106, v106 row_half_mirror row_mask:0xf bank_mask:0xf bound_ctrl:1
	v_add_f32_dpp v107, v107, v107 row_half_mirror row_mask:0xf bank_mask:0xf bound_ctrl:1
	v_pk_mul_f32 v[144:145], v[68:69], v[42:43] op_sel_hi:[1,0]
	v_pk_mul_f32 v[146:147], v[70:71], v[42:43] op_sel:[0,1]
	v_add_f32_dpp v106, v106, v106 row_mirror row_mask:0xf bank_mask:0xf bound_ctrl:1
	v_add_f32_dpp v107, v107, v107 row_mirror row_mask:0xf bank_mask:0xf bound_ctrl:1
	v_pk_fma_f32 v[110:111], v[60:61], v[52:53], v[110:111] op_sel_hi:[1,0,1]
	v_pk_fma_f32 v[112:113], v[60:61], v[52:53], v[112:113] op_sel:[0,1,0]
	v_pk_fma_f32 v[144:145], v[60:61], v[54:55], v[144:145] op_sel_hi:[1,0,1]
	v_pk_fma_f32 v[146:147], v[60:61], v[54:55], v[146:147] op_sel:[0,1,0]
	v_pk_fma_f32 v[64:65], v[106:107], v[48:49], v[110:111] op_sel_hi:[1,0,1]
	v_pk_fma_f32 v[66:67], v[106:107], v[48:49], v[112:113] op_sel:[0,1,0]
	v_pk_fma_f32 v[68:69], v[106:107], v[50:51], v[144:145] op_sel_hi:[1,0,1]
	v_pk_fma_f32 v[70:71], v[106:107], v[50:51], v[146:147] op_sel:[0,1,0]
	s_waitcnt lgkmcnt(0)
	ds_read_b128 v[40:43], v175 offset:28160
	ds_read_b128 v[44:47], v175 offset:28176
	ds_read_b128 v[48:51], v175 offset:28192
	ds_read_b128 v[52:55], v175 offset:28208
	ds_read_b128 v[56:59], v175 offset:28224
	ds_read_b128 v[60:63], v123 offset:46592
	v_pk_mul_f32 v[106:107], v[64:65], v[76:77] op_sel_hi:[1,0]
	v_pk_mul_f32 v[108:109], v[64:65], v[88:89] op_sel_hi:[1,0]
	v_pk_fma_f32 v[106:107], v[66:67], v[76:77], v[106:107] op_sel:[0,1,0]
	v_pk_fma_f32 v[108:109], v[66:67], v[88:89], v[108:109] op_sel:[0,1,0]
	v_pk_fma_f32 v[106:107], v[68:69], v[78:79], v[106:107] op_sel_hi:[1,0,1]
	v_pk_fma_f32 v[108:109], v[68:69], v[90:91], v[108:109] op_sel_hi:[1,0,1]
	v_pk_fma_f32 v[106:107], v[70:71], v[78:79], v[106:107] op_sel:[0,1,0]
	v_pk_fma_f32 v[108:109], v[70:71], v[90:91], v[108:109] op_sel:[0,1,0]
	v_pk_mul_f32 v[110:111], v[64:65], v[72:73] op_sel_hi:[1,0]
	v_add_f32_dpp v106, v106, v106 quad_perm:[1,0,3,2] row_mask:0xf bank_mask:0xf bound_ctrl:1
	v_add_f32_dpp v107, v107, v107 quad_perm:[1,0,3,2] row_mask:0xf bank_mask:0xf bound_ctrl:1
	v_pk_fma_f32 v[108:109], v[94:95], v[176:177], v[108:109]
	v_pk_mul_f32 v[112:113], v[66:67], v[72:73] op_sel:[0,1]
	v_add_f32_dpp v106, v106, v106 quad_perm:[2,3,0,1] row_mask:0xf bank_mask:0xf bound_ctrl:1
	v_add_f32_dpp v107, v107, v107 quad_perm:[2,3,0,1] row_mask:0xf bank_mask:0xf bound_ctrl:1
	v_add_f32_dpp v149, v108, v108 row_half_mirror row_mask:0xf bank_mask:0xf bound_ctrl:1
	v_add_f32_dpp v149, v109, v109 row_half_mirror row_mask:0xf bank_mask:0xa
	v_add_f32_dpp v106, v106, v106 row_half_mirror row_mask:0xf bank_mask:0xf bound_ctrl:1
	v_add_f32_dpp v107, v107, v107 row_half_mirror row_mask:0xf bank_mask:0xf bound_ctrl:1
	v_pk_mul_f32 v[144:145], v[68:69], v[74:75] op_sel_hi:[1,0]
	v_pk_mul_f32 v[146:147], v[70:71], v[74:75] op_sel:[0,1]
	v_add_f32_dpp v150, v148, v148 row_ror:8 row_mask:0xf bank_mask:0xf bound_ctrl:1
	v_add_f32_dpp v150, v149, v149 row_ror:8 row_mask:0xf bank_mask:0xc
	v_add_f32_dpp v106, v106, v106 row_mirror row_mask:0xf bank_mask:0xf bound_ctrl:1
	v_add_f32_dpp v107, v107, v107 row_mirror row_mask:0xf bank_mask:0xf bound_ctrl:1
	v_pk_fma_f32 v[110:111], v[92:93], v[84:85], v[110:111] op_sel_hi:[1,0,1]
	v_pk_fma_f32 v[112:113], v[92:93], v[84:85], v[112:113] op_sel:[0,1,0]
	v_pk_fma_f32 v[144:145], v[92:93], v[86:87], v[144:145] op_sel_hi:[1,0,1]
	v_pk_fma_f32 v[146:147], v[92:93], v[86:87], v[146:147] op_sel:[0,1,0]
	v_add_f32_dpp v150, v150, v150 quad_perm:[1,0,3,2] row_mask:0xf bank_mask:0xf bound_ctrl:1
	v_pk_fma_f32 v[64:65], v[106:107], v[80:81], v[110:111] op_sel_hi:[1,0,1]
	v_pk_fma_f32 v[66:67], v[106:107], v[80:81], v[112:113] op_sel:[0,1,0]
	v_add_f32_dpp v150, v150, v150 quad_perm:[2,3,0,1] row_mask:0xf bank_mask:0xf bound_ctrl:1
	v_pk_fma_f32 v[68:69], v[106:107], v[82:83], v[144:145] op_sel_hi:[1,0,1]
	v_pk_fma_f32 v[70:71], v[106:107], v[82:83], v[146:147] op_sel:[0,1,0]
	ds_write_b32 v178, v150 offset:2560
	s_waitcnt lgkmcnt(1)
; #define SC_GET(X, t) do { const float* p = rec + (t) * 320; w##X = *(const f32x4*)p; a##X = *(const f32x4*)(p + 4); b##X = *(const f32x4*)(p + 8); k##X = *(const f32x4*)(p + 12); q##X = *(const f32x4*)(p + 16); \
;                 v##X = *(const f32x4*)(VVa + (t) * 64); } while (0)
; DI void scan_phase(unsigned char* lds, const Ctx& a, const Op& d, const int variant) {
;     ...
;                 SC_GET(A, 0);
; #pragma unroll 2
;                 for (int t = 0; t < SC_T; t += 2) {
;                     SC_GET(B, t + 1);
;                     SC_STEP(A, t);
;                     if (t + 2 < SC_T) SC_GET(A, t + 2);
;                     SC_STEP(B, t + 1);
;                 }
	ds_read_b128 v[72:75], v175 offset:29440
	ds_read_b128 v[76:79], v175 offset:29456
	ds_read_b128 v[80:83], v175 offset:29472
	ds_read_b128 v[84:87], v175 offset:29488
	ds_read_b128 v[88:91], v175 offset:29504
	ds_read_b128 v[92:95], v123 offset:46848
	v_pk_mul_f32 v[106:107], v[64:65], v[44:45] op_sel_hi:[1,0]
	v_pk_mul_f32 v[108:109], v[64:65], v[56:57] op_sel_hi:[1,0]
	v_pk_fma_f32 v[106:107], v[66:67], v[44:45], v[106:107] op_sel:[0,1,0]
	v_pk_fma_f32 v[108:109], v[66:67], v[56:57], v[108:109] op_sel:[0,1,0]
	v_pk_fma_f32 v[106:107], v[68:69], v[46:47], v[106:107] op_sel_hi:[1,0,1]
	v_pk_fma_f32 v[108:109], v[68:69], v[58:59], v[108:109] op_sel_hi:[1,0,1]
	v_pk_fma_f32 v[106:107], v[70:71], v[46:47], v[106:107] op_sel:[0,1,0]
	v_pk_fma_f32 v[108:109], v[70:71], v[58:59], v[108:109] op_sel:[0,1,0]
	v_pk_mul_f32 v[110:111], v[64:65], v[40:41] op_sel_hi:[1,0]
	v_add_f32_dpp v106, v106, v106 quad_perm:[1,0,3,2] row_mask:0xf bank_mask:0xf bound_ctrl:1
	v_add_f32_dpp v107, v107, v107 quad_perm:[1,0,3,2] row_mask:0xf bank_mask:0xf bound_ctrl:1
	v_pk_fma_f32 v[108:109], v[62:63], v[176:177], v[108:109]
	v_pk_mul_f32 v[112:113], v[66:67], v[40:41] op_sel:[0,1]
	v_add_f32_dpp v106, v106, v106 quad_perm:[2,3,0,1] row_mask:0xf bank_mask:0xf bound_ctrl:1
	v_add_f32_dpp v107, v107, v107 quad_perm:[2,3,0,1] row_mask:0xf bank_mask:0xf bound_ctrl:1
	v_add_f32_dpp v148, v108, v108 row_half_mirror row_mask:0xf bank_mask:0xf bound_ctrl:1
	v_add_f32_dpp v148, v109, v109 row_half_mirror row_mask:0xf bank_mask:0xa
	v_add_f32_dpp v106, v106, v106 row_half_mirror row_mask:0xf bank_mask:0xf bound_ctrl:1
	v_add_f32_dpp v107, v107, v107 row_half_mirror row_mask:0xf bank_mask:0xf bound_ctrl:1
	v_pk_mul_f32 v[144:145], v[68:69], v[42:43] op_sel_hi:[1,0]
	v_pk_mul_f32 v[146:147], v[70:71], v[42:43] op_sel:[0,1]
	v_add_f32_dpp v106, v106, v106 row_mirror row_mask:0xf bank_mask:0xf bound_ctrl:1
	v_add_f32_dpp v107, v107, v107 row_mirror row_mask:0xf bank_mask:0xf bound_ctrl:1
	v_pk_fma_f32 v[110:111], v[60:61], v[52:53], v[110:111] op_sel_hi:[1,0,1]
	v_pk_fma_f32 v[112:113], v[60:61], v[52:53], v[112:113] op_sel:[0,1,0]
	v_pk_fma_f32 v[144:145], v[60:61], v[54:55], v[144:145] op_sel_hi:[1,0,1]
	v_pk_fma_f32 v[146:147], v[60:61], v[54:55], v[146:147] op_sel:[0,1,0]
	v_pk_fma_f32 v[64:65], v[106:107], v[48:49], v[110:111] op_sel_hi:[1,0,1]
	v_pk_fma_f32 v[66:67], v[106:107], v[48:49], v[112:113] op_sel:[0,1,0]
	v_pk_fma_f32 v[68:69], v[106:107], v[50:51], v[144:145] op_sel_hi:[1,0,1]
	v_pk_fma_f32 v[70:71], v[106:107], v[50:51], v[146:147] op_sel:[0,1,0]
	s_waitcnt lgkmcnt(0)
	ds_read_b128 v[40:43], v175 offset:30720
	ds_read_b128 v[44:47], v175 offset:30736
	ds_read_b128 v[48:51], v175 offset:30752
	ds_read_b128 v[52:55], v175 offset:30768
	ds_read_b128 v[56:59], v175 offset:30784
	ds_read_b128 v[60:63], v123 offset:47104
	v_pk_mul_f32 v[106:107], v[64:65], v[76:77] op_sel_hi:[1,0]
	v_pk_mul_f32 v[108:109], v[64:65], v[88:89] op_sel_hi:[1,0]
	v_pk_fma_f32 v[106:107], v[66:67], v[76:77], v[106:107] op_sel:[0,1,0]
	v_pk_fma_f32 v[108:109], v[66:67], v[88:89], v[108:109] op_sel:[0,1,0]
	v_pk_fma_f32 v[106:107], v[68:69], v[78:79], v[106:107] op_sel_hi:[1,0,1]
	v_pk_fma_f32 v[108:109], v[68:69], v[90:91], v[108:109] op_sel_hi:[1,0,1]
	v_pk_fma_f32 v[106:107], v[70:71], v[78:79], v[106:107] op_sel:[0,1,0]
	v_pk_fma_f32 v[108:109], v[70:71], v[90:91], v[108:109] op_sel:[0,1,0]
	v_pk_mul_f32 v[110:111], v[64:65], v[72:73] op_sel_hi:[1,0]
	v_add_f32_dpp v106, v106, v106 quad_perm:[1,0,3,2] row_mask:0xf bank_mask:0xf bound_ctrl:1
	v_add_f32_dpp v107, v107, v107 quad_perm:[1,0,3,2] row_mask:0xf bank_mask:0xf bound_ctrl:1
	v_pk_fma_f32 v[108:109], v[94:95], v[176:177], v[108:109]
	v_pk_mul_f32 v[112:113], v[66:67], v[72:73] op_sel:[0,1]
	v_add_f32_dpp v106, v106, v106 quad_perm:[2,3,0,1] row_mask:0xf bank_mask:0xf bound_ctrl:1
	v_add_f32_dpp v107, v107, v107 quad_perm:[2,3,0,1] row_mask:0xf bank_mask:0xf bound_ctrl:1
	v_add_f32_dpp v149, v108, v108 row_half_mirror row_mask:0xf bank_mask:0xf bound_ctrl:1
	v_add_f32_dpp v149, v109, v109 row_half_mirror row_mask:0xf bank_mask:0xa
	v_add_f32_dpp v106, v106, v106 row_half_mirror row_mask:0xf bank_mask:0xf bound_ctrl:1
	v_add_f32_dpp v107, v107, v107 row_half_mirror row_mask:0xf bank_mask:0xf bound_ctrl:1
	v_pk_mul_f32 v[144:145], v[68:69], v[74:75] op_sel_hi:[1,0]
	v_pk_mul_f32 v[146:147], v[70:71], v[74:75] op_sel:[0,1]
	v_add_f32_dpp v150, v148, v148 row_ror:8 row_mask:0xf bank_mask:0xf bound_ctrl:1
	v_add_f32_dpp v150, v149, v149 row_ror:8 row_mask:0xf bank_mask:0xc
	v_add_f32_dpp v106, v106, v106 row_mirror row_mask:0xf bank_mask:0xf bound_ctrl:1
	v_add_f32_dpp v107, v107, v107 row_mirror row_mask:0xf bank_mask:0xf bound_ctrl:1
	v_pk_fma_f32 v[110:111], v[92:93], v[84:85], v[110:111] op_sel_hi:[1,0,1]
	v_pk_fma_f32 v[112:113], v[92:93], v[84:85], v[112:113] op_sel:[0,1,0]
	v_pk_fma_f32 v[144:145], v[92:93], v[86:87], v[144:145] op_sel_hi:[1,0,1]
	v_pk_fma_f32 v[146:147], v[92:93], v[86:87], v[146:147] op_sel:[0,1,0]
	v_add_f32_dpp v150, v150, v150 quad_perm:[1,0,3,2] row_mask:0xf bank_mask:0xf bound_ctrl:1
	v_pk_fma_f32 v[64:65], v[106:107], v[80:81], v[110:111] op_sel_hi:[1,0,1]
	v_pk_fma_f32 v[66:67], v[106:107], v[80:81], v[112:113] op_sel:[0,1,0]
	v_add_f32_dpp v150, v150, v150 quad_perm:[2,3,0,1] row_mask:0xf bank_mask:0xf bound_ctrl:1
	v_pk_fma_f32 v[68:69], v[106:107], v[82:83], v[144:145] op_sel_hi:[1,0,1]
	v_pk_fma_f32 v[70:71], v[106:107], v[82:83], v[146:147] op_sel:[0,1,0]
	ds_write_b32 v178, v150 offset:2816
	s_waitcnt lgkmcnt(1)
; #define SC_GET(X, t) do { const float* p = rec + (t) * 320; w##X = *(const f32x4*)p; a##X = *(const f32x4*)(p + 4); b##X = *(const f32x4*)(p + 8); k##X = *(const f32x4*)(p + 12); q##X = *(const f32x4*)(p + 16); \
;                 v##X = *(const f32x4*)(VVa + (t) * 64); } while (0)
; DI void scan_phase(unsigned char* lds, const Ctx& a, const Op& d, const int variant) {
;     ...
;                 SC_GET(A, 0);
; #pragma unroll 2
;                 for (int t = 0; t < SC_T; t += 2) {
;                     SC_GET(B, t + 1);
;                     SC_STEP(A, t);
;                     if (t + 2 < SC_T) SC_GET(A, t + 2);
;                     SC_STEP(B, t + 1);
;                 }
	ds_read_b128 v[72:75], v175 offset:32000
	ds_read_b128 v[76:79], v175 offset:32016
	ds_read_b128 v[80:83], v175 offset:32032
	ds_read_b128 v[84:87], v175 offset:32048
	ds_read_b128 v[88:91], v175 offset:32064
	ds_read_b128 v[92:95], v123 offset:47360
	v_pk_mul_f32 v[106:107], v[64:65], v[44:45] op_sel_hi:[1,0]
	v_pk_mul_f32 v[108:109], v[64:65], v[56:57] op_sel_hi:[1,0]
	v_pk_fma_f32 v[106:107], v[66:67], v[44:45], v[106:107] op_sel:[0,1,0]
	v_pk_fma_f32 v[108:109], v[66:67], v[56:57], v[108:109] op_sel:[0,1,0]
	v_pk_fma_f32 v[106:107], v[68:69], v[46:47], v[106:107] op_sel_hi:[1,0,1]
	v_pk_fma_f32 v[108:109], v[68:69], v[58:59], v[108:109] op_sel_hi:[1,0,1]
	v_pk_fma_f32 v[106:107], v[70:71], v[46:47], v[106:107] op_sel:[0,1,0]
	v_pk_fma_f32 v[108:109], v[70:71], v[58:59], v[108:109] op_sel:[0,1,0]
	v_pk_mul_f32 v[110:111], v[64:65], v[40:41] op_sel_hi:[1,0]
	v_add_f32_dpp v106, v106, v106 quad_perm:[1,0,3,2] row_mask:0xf bank_mask:0xf bound_ctrl:1
	v_add_f32_dpp v107, v107, v107 quad_perm:[1,0,3,2] row_mask:0xf bank_mask:0xf bound_ctrl:1
	v_pk_fma_f32 v[108:109], v[62:63], v[176:177], v[108:109]
	v_pk_mul_f32 v[112:113], v[66:67], v[40:41] op_sel:[0,1]
	v_add_f32_dpp v106, v106, v106 quad_perm:[2,3,0,1] row_mask:0xf bank_mask:0xf bound_ctrl:1
	v_add_f32_dpp v107, v107, v107 quad_perm:[2,3,0,1] row_mask:0xf bank_mask:0xf bound_ctrl:1
	v_add_f32_dpp v148, v108, v108 row_half_mirror row_mask:0xf bank_mask:0xf bound_ctrl:1
	v_add_f32_dpp v148, v109, v109 row_half_mirror row_mask:0xf bank_mask:0xa
	v_add_f32_dpp v106, v106, v106 row_half_mirror row_mask:0xf bank_mask:0xf bound_ctrl:1
	v_add_f32_dpp v107, v107, v107 row_half_mirror row_mask:0xf bank_mask:0xf bound_ctrl:1
	v_pk_mul_f32 v[144:145], v[68:69], v[42:43] op_sel_hi:[1,0]
	v_pk_mul_f32 v[146:147], v[70:71], v[42:43] op_sel:[0,1]
	v_add_f32_dpp v106, v106, v106 row_mirror row_mask:0xf bank_mask:0xf bound_ctrl:1
	v_add_f32_dpp v107, v107, v107 row_mirror row_mask:0xf bank_mask:0xf bound_ctrl:1
	v_pk_fma_f32 v[110:111], v[60:61], v[52:53], v[110:111] op_sel_hi:[1,0,1]
	v_pk_fma_f32 v[112:113], v[60:61], v[52:53], v[112:113] op_sel:[0,1,0]
	v_pk_fma_f32 v[144:145], v[60:61], v[54:55], v[144:145] op_sel_hi:[1,0,1]
	v_pk_fma_f32 v[146:147], v[60:61], v[54:55], v[146:147] op_sel:[0,1,0]
	v_pk_fma_f32 v[64:65], v[106:107], v[48:49], v[110:111] op_sel_hi:[1,0,1]
	v_pk_fma_f32 v[66:67], v[106:107], v[48:49], v[112:113] op_sel:[0,1,0]
	v_pk_fma_f32 v[68:69], v[106:107], v[50:51], v[144:145] op_sel_hi:[1,0,1]
	v_pk_fma_f32 v[70:71], v[106:107], v[50:51], v[146:147] op_sel:[0,1,0]
	s_waitcnt lgkmcnt(0)
	ds_read_b128 v[40:43], v175 offset:33280
	ds_read_b128 v[44:47], v175 offset:33296
	ds_read_b128 v[48:51], v175 offset:33312
	ds_read_b128 v[52:55], v175 offset:33328
	ds_read_b128 v[56:59], v175 offset:33344
	ds_read_b128 v[60:63], v123 offset:47616
	v_pk_mul_f32 v[106:107], v[64:65], v[76:77] op_sel_hi:[1,0]
	v_pk_mul_f32 v[108:109], v[64:65], v[88:89] op_sel_hi:[1,0]
	v_pk_fma_f32 v[106:107], v[66:67], v[76:77], v[106:107] op_sel:[0,1,0]
	v_pk_fma_f32 v[108:109], v[66:67], v[88:89], v[108:109] op_sel:[0,1,0]
	v_pk_fma_f32 v[106:107], v[68:69], v[78:79], v[106:107] op_sel_hi:[1,0,1]
	v_pk_fma_f32 v[108:109], v[68:69], v[90:91], v[108:109] op_sel_hi:[1,0,1]
	v_pk_fma_f32 v[106:107], v[70:71], v[78:79], v[106:107] op_sel:[0,1,0]
	v_pk_fma_f32 v[108:109], v[70:71], v[90:91], v[108:109] op_sel:[0,1,0]
	v_pk_mul_f32 v[110:111], v[64:65], v[72:73] op_sel_hi:[1,0]
	v_add_f32_dpp v106, v106, v106 quad_perm:[1,0,3,2] row_mask:0xf bank_mask:0xf bound_ctrl:1
	v_add_f32_dpp v107, v107, v107 quad_perm:[1,0,3,2] row_mask:0xf bank_mask:0xf bound_ctrl:1
	v_pk_fma_f32 v[108:109], v[94:95], v[176:177], v[108:109]
	v_pk_mul_f32 v[112:113], v[66:67], v[72:73] op_sel:[0,1]
	v_add_f32_dpp v106, v106, v106 quad_perm:[2,3,0,1] row_mask:0xf bank_mask:0xf bound_ctrl:1
	v_add_f32_dpp v107, v107, v107 quad_perm:[2,3,0,1] row_mask:0xf bank_mask:0xf bound_ctrl:1
	v_add_f32_dpp v149, v108, v108 row_half_mirror row_mask:0xf bank_mask:0xf bound_ctrl:1
	v_add_f32_dpp v149, v109, v109 row_half_mirror row_mask:0xf bank_mask:0xa
	v_add_f32_dpp v106, v106, v106 row_half_mirror row_mask:0xf bank_mask:0xf bound_ctrl:1
	v_add_f32_dpp v107, v107, v107 row_half_mirror row_mask:0xf bank_mask:0xf bound_ctrl:1
	v_pk_mul_f32 v[144:145], v[68:69], v[74:75] op_sel_hi:[1,0]
	v_pk_mul_f32 v[146:147], v[70:71], v[74:75] op_sel:[0,1]
	v_add_f32_dpp v150, v148, v148 row_ror:8 row_mask:0xf bank_mask:0xf bound_ctrl:1
	v_add_f32_dpp v150, v149, v149 row_ror:8 row_mask:0xf bank_mask:0xc
	v_add_f32_dpp v106, v106, v106 row_mirror row_mask:0xf bank_mask:0xf bound_ctrl:1
	v_add_f32_dpp v107, v107, v107 row_mirror row_mask:0xf bank_mask:0xf bound_ctrl:1
	v_pk_fma_f32 v[110:111], v[92:93], v[84:85], v[110:111] op_sel_hi:[1,0,1]
	v_pk_fma_f32 v[112:113], v[92:93], v[84:85], v[112:113] op_sel:[0,1,0]
	v_pk_fma_f32 v[144:145], v[92:93], v[86:87], v[144:145] op_sel_hi:[1,0,1]
	v_pk_fma_f32 v[146:147], v[92:93], v[86:87], v[146:147] op_sel:[0,1,0]
	v_add_f32_dpp v150, v150, v150 quad_perm:[1,0,3,2] row_mask:0xf bank_mask:0xf bound_ctrl:1
	v_pk_fma_f32 v[64:65], v[106:107], v[80:81], v[110:111] op_sel_hi:[1,0,1]
	v_pk_fma_f32 v[66:67], v[106:107], v[80:81], v[112:113] op_sel:[0,1,0]
	v_add_f32_dpp v150, v150, v150 quad_perm:[2,3,0,1] row_mask:0xf bank_mask:0xf bound_ctrl:1
	v_pk_fma_f32 v[68:69], v[106:107], v[82:83], v[144:145] op_sel_hi:[1,0,1]
	v_pk_fma_f32 v[70:71], v[106:107], v[82:83], v[146:147] op_sel:[0,1,0]
	ds_write_b32 v178, v150 offset:3072
	s_waitcnt lgkmcnt(1)
; #define SC_GET(X, t) do { const float* p = rec + (t) * 320; w##X = *(const f32x4*)p; a##X = *(const f32x4*)(p + 4); b##X = *(const f32x4*)(p + 8); k##X = *(const f32x4*)(p + 12); q##X = *(const f32x4*)(p + 16); \
;                 v##X = *(const f32x4*)(VVa + (t) * 64); } while (0)
; DI void scan_phase(unsigned char* lds, const Ctx& a, const Op& d, const int variant) {
;     ...
;                 SC_GET(A, 0);
; #pragma unroll 2
;                 for (int t = 0; t < SC_T; t += 2) {
;                     SC_GET(B, t + 1);
;                     SC_STEP(A, t);
;                     if (t + 2 < SC_T) SC_GET(A, t + 2);
;                     SC_STEP(B, t + 1);
;                 }
	ds_read_b128 v[72:75], v175 offset:34560
	ds_read_b128 v[76:79], v175 offset:34576
	ds_read_b128 v[80:83], v175 offset:34592
	ds_read_b128 v[84:87], v175 offset:34608
	ds_read_b128 v[88:91], v175 offset:34624
	ds_read_b128 v[92:95], v123 offset:47872
	v_pk_mul_f32 v[106:107], v[64:65], v[44:45] op_sel_hi:[1,0]
	v_pk_mul_f32 v[108:109], v[64:65], v[56:57] op_sel_hi:[1,0]
	v_pk_fma_f32 v[106:107], v[66:67], v[44:45], v[106:107] op_sel:[0,1,0]
	v_pk_fma_f32 v[108:109], v[66:67], v[56:57], v[108:109] op_sel:[0,1,0]
	v_pk_fma_f32 v[106:107], v[68:69], v[46:47], v[106:107] op_sel_hi:[1,0,1]
	v_pk_fma_f32 v[108:109], v[68:69], v[58:59], v[108:109] op_sel_hi:[1,0,1]
	v_pk_fma_f32 v[106:107], v[70:71], v[46:47], v[106:107] op_sel:[0,1,0]
	v_pk_fma_f32 v[108:109], v[70:71], v[58:59], v[108:109] op_sel:[0,1,0]
	v_pk_mul_f32 v[110:111], v[64:65], v[40:41] op_sel_hi:[1,0]
	v_add_f32_dpp v106, v106, v106 quad_perm:[1,0,3,2] row_mask:0xf bank_mask:0xf bound_ctrl:1
	v_add_f32_dpp v107, v107, v107 quad_perm:[1,0,3,2] row_mask:0xf bank_mask:0xf bound_ctrl:1
	v_pk_fma_f32 v[108:109], v[62:63], v[176:177], v[108:109]
	v_pk_mul_f32 v[112:113], v[66:67], v[40:41] op_sel:[0,1]
	v_add_f32_dpp v106, v106, v106 quad_perm:[2,3,0,1] row_mask:0xf bank_mask:0xf bound_ctrl:1
	v_add_f32_dpp v107, v107, v107 quad_perm:[2,3,0,1] row_mask:0xf bank_mask:0xf bound_ctrl:1
	v_add_f32_dpp v148, v108, v108 row_half_mirror row_mask:0xf bank_mask:0xf bound_ctrl:1
	v_add_f32_dpp v148, v109, v109 row_half_mirror row_mask:0xf bank_mask:0xa
	v_add_f32_dpp v106, v106, v106 row_half_mirror row_mask:0xf bank_mask:0xf bound_ctrl:1
	v_add_f32_dpp v107, v107, v107 row_half_mirror row_mask:0xf bank_mask:0xf bound_ctrl:1
	v_pk_mul_f32 v[144:145], v[68:69], v[42:43] op_sel_hi:[1,0]
	v_pk_mul_f32 v[146:147], v[70:71], v[42:43] op_sel:[0,1]
	v_add_f32_dpp v106, v106, v106 row_mirror row_mask:0xf bank_mask:0xf bound_ctrl:1
	v_add_f32_dpp v107, v107, v107 row_mirror row_mask:0xf bank_mask:0xf bound_ctrl:1
	v_pk_fma_f32 v[110:111], v[60:61], v[52:53], v[110:111] op_sel_hi:[1,0,1]
	v_pk_fma_f32 v[112:113], v[60:61], v[52:53], v[112:113] op_sel:[0,1,0]
	v_pk_fma_f32 v[144:145], v[60:61], v[54:55], v[144:145] op_sel_hi:[1,0,1]
	v_pk_fma_f32 v[146:147], v[60:61], v[54:55], v[146:147] op_sel:[0,1,0]
	v_pk_fma_f32 v[64:65], v[106:107], v[48:49], v[110:111] op_sel_hi:[1,0,1]
	v_pk_fma_f32 v[66:67], v[106:107], v[48:49], v[112:113] op_sel:[0,1,0]
	v_pk_fma_f32 v[68:69], v[106:107], v[50:51], v[144:145] op_sel_hi:[1,0,1]
	v_pk_fma_f32 v[70:71], v[106:107], v[50:51], v[146:147] op_sel:[0,1,0]
	s_waitcnt lgkmcnt(0)
	ds_read_b128 v[40:43], v175 offset:35840
	ds_read_b128 v[44:47], v175 offset:35856
	ds_read_b128 v[48:51], v175 offset:35872
	ds_read_b128 v[52:55], v175 offset:35888
	ds_read_b128 v[56:59], v175 offset:35904
	ds_read_b128 v[60:63], v123 offset:48128
	v_pk_mul_f32 v[106:107], v[64:65], v[76:77] op_sel_hi:[1,0]
	v_pk_mul_f32 v[108:109], v[64:65], v[88:89] op_sel_hi:[1,0]
	v_pk_fma_f32 v[106:107], v[66:67], v[76:77], v[106:107] op_sel:[0,1,0]
	v_pk_fma_f32 v[108:109], v[66:67], v[88:89], v[108:109] op_sel:[0,1,0]
	v_pk_fma_f32 v[106:107], v[68:69], v[78:79], v[106:107] op_sel_hi:[1,0,1]
	v_pk_fma_f32 v[108:109], v[68:69], v[90:91], v[108:109] op_sel_hi:[1,0,1]
	v_pk_fma_f32 v[106:107], v[70:71], v[78:79], v[106:107] op_sel:[0,1,0]
	v_pk_fma_f32 v[108:109], v[70:71], v[90:91], v[108:109] op_sel:[0,1,0]
	v_pk_mul_f32 v[110:111], v[64:65], v[72:73] op_sel_hi:[1,0]
	v_add_f32_dpp v106, v106, v106 quad_perm:[1,0,3,2] row_mask:0xf bank_mask:0xf bound_ctrl:1
	v_add_f32_dpp v107, v107, v107 quad_perm:[1,0,3,2] row_mask:0xf bank_mask:0xf bound_ctrl:1
	v_pk_fma_f32 v[108:109], v[94:95], v[176:177], v[108:109]
	v_pk_mul_f32 v[112:113], v[66:67], v[72:73] op_sel:[0,1]
	v_add_f32_dpp v106, v106, v106 quad_perm:[2,3,0,1] row_mask:0xf bank_mask:0xf bound_ctrl:1
	v_add_f32_dpp v107, v107, v107 quad_perm:[2,3,0,1] row_mask:0xf bank_mask:0xf bound_ctrl:1
	v_add_f32_dpp v149, v108, v108 row_half_mirror row_mask:0xf bank_mask:0xf bound_ctrl:1
	v_add_f32_dpp v149, v109, v109 row_half_mirror row_mask:0xf bank_mask:0xa
	v_add_f32_dpp v106, v106, v106 row_half_mirror row_mask:0xf bank_mask:0xf bound_ctrl:1
	v_add_f32_dpp v107, v107, v107 row_half_mirror row_mask:0xf bank_mask:0xf bound_ctrl:1
	v_pk_mul_f32 v[144:145], v[68:69], v[74:75] op_sel_hi:[1,0]
	v_pk_mul_f32 v[146:147], v[70:71], v[74:75] op_sel:[0,1]
	v_add_f32_dpp v150, v148, v148 row_ror:8 row_mask:0xf bank_mask:0xf bound_ctrl:1
	v_add_f32_dpp v150, v149, v149 row_ror:8 row_mask:0xf bank_mask:0xc
	v_add_f32_dpp v106, v106, v106 row_mirror row_mask:0xf bank_mask:0xf bound_ctrl:1
	v_add_f32_dpp v107, v107, v107 row_mirror row_mask:0xf bank_mask:0xf bound_ctrl:1
	v_pk_fma_f32 v[110:111], v[92:93], v[84:85], v[110:111] op_sel_hi:[1,0,1]
	v_pk_fma_f32 v[112:113], v[92:93], v[84:85], v[112:113] op_sel:[0,1,0]
	v_pk_fma_f32 v[144:145], v[92:93], v[86:87], v[144:145] op_sel_hi:[1,0,1]
	v_pk_fma_f32 v[146:147], v[92:93], v[86:87], v[146:147] op_sel:[0,1,0]
	v_add_f32_dpp v150, v150, v150 quad_perm:[1,0,3,2] row_mask:0xf bank_mask:0xf bound_ctrl:1
	v_pk_fma_f32 v[64:65], v[106:107], v[80:81], v[110:111] op_sel_hi:[1,0,1]
	v_pk_fma_f32 v[66:67], v[106:107], v[80:81], v[112:113] op_sel:[0,1,0]
	v_add_f32_dpp v150, v150, v150 quad_perm:[2,3,0,1] row_mask:0xf bank_mask:0xf bound_ctrl:1
	v_pk_fma_f32 v[68:69], v[106:107], v[82:83], v[144:145] op_sel_hi:[1,0,1]
	v_pk_fma_f32 v[70:71], v[106:107], v[82:83], v[146:147] op_sel:[0,1,0]
	ds_write_b32 v178, v150 offset:3328
	s_waitcnt lgkmcnt(1)
; #define SC_GET(X, t) do { const float* p = rec + (t) * 320; w##X = *(const f32x4*)p; a##X = *(const f32x4*)(p + 4); b##X = *(const f32x4*)(p + 8); k##X = *(const f32x4*)(p + 12); q##X = *(const f32x4*)(p + 16); \
;                 v##X = *(const f32x4*)(VVa + (t) * 64); } while (0)
; DI void scan_phase(unsigned char* lds, const Ctx& a, const Op& d, const int variant) {
;     ...
;                 SC_GET(A, 0);
; #pragma unroll 2
;                 for (int t = 0; t < SC_T; t += 2) {
;                     SC_GET(B, t + 1);
;                     SC_STEP(A, t);
;                     if (t + 2 < SC_T) SC_GET(A, t + 2);
;                     SC_STEP(B, t + 1);
;                 }
	ds_read_b128 v[72:75], v175 offset:37120
	ds_read_b128 v[76:79], v175 offset:37136
	ds_read_b128 v[80:83], v175 offset:37152
	ds_read_b128 v[84:87], v175 offset:37168
	ds_read_b128 v[88:91], v175 offset:37184
	ds_read_b128 v[92:95], v123 offset:48384
	v_pk_mul_f32 v[106:107], v[64:65], v[44:45] op_sel_hi:[1,0]
	v_pk_mul_f32 v[108:109], v[64:65], v[56:57] op_sel_hi:[1,0]
	v_pk_fma_f32 v[106:107], v[66:67], v[44:45], v[106:107] op_sel:[0,1,0]
	v_pk_fma_f32 v[108:109], v[66:67], v[56:57], v[108:109] op_sel:[0,1,0]
	v_pk_fma_f32 v[106:107], v[68:69], v[46:47], v[106:107] op_sel_hi:[1,0,1]
	v_pk_fma_f32 v[108:109], v[68:69], v[58:59], v[108:109] op_sel_hi:[1,0,1]
	v_pk_fma_f32 v[106:107], v[70:71], v[46:47], v[106:107] op_sel:[0,1,0]
	v_pk_fma_f32 v[108:109], v[70:71], v[58:59], v[108:109] op_sel:[0,1,0]
	v_pk_mul_f32 v[110:111], v[64:65], v[40:41] op_sel_hi:[1,0]
	v_add_f32_dpp v106, v106, v106 quad_perm:[1,0,3,2] row_mask:0xf bank_mask:0xf bound_ctrl:1
	v_add_f32_dpp v107, v107, v107 quad_perm:[1,0,3,2] row_mask:0xf bank_mask:0xf bound_ctrl:1
	v_pk_fma_f32 v[108:109], v[62:63], v[176:177], v[108:109]
	v_pk_mul_f32 v[112:113], v[66:67], v[40:41] op_sel:[0,1]
	v_add_f32_dpp v106, v106, v106 quad_perm:[2,3,0,1] row_mask:0xf bank_mask:0xf bound_ctrl:1
	v_add_f32_dpp v107, v107, v107 quad_perm:[2,3,0,1] row_mask:0xf bank_mask:0xf bound_ctrl:1
	v_add_f32_dpp v148, v108, v108 row_half_mirror row_mask:0xf bank_mask:0xf bound_ctrl:1
	v_add_f32_dpp v148, v109, v109 row_half_mirror row_mask:0xf bank_mask:0xa
	v_add_f32_dpp v106, v106, v106 row_half_mirror row_mask:0xf bank_mask:0xf bound_ctrl:1
	v_add_f32_dpp v107, v107, v107 row_half_mirror row_mask:0xf bank_mask:0xf bound_ctrl:1
	v_pk_mul_f32 v[144:145], v[68:69], v[42:43] op_sel_hi:[1,0]
	v_pk_mul_f32 v[146:147], v[70:71], v[42:43] op_sel:[0,1]
	v_add_f32_dpp v106, v106, v106 row_mirror row_mask:0xf bank_mask:0xf bound_ctrl:1
	v_add_f32_dpp v107, v107, v107 row_mirror row_mask:0xf bank_mask:0xf bound_ctrl:1
	v_pk_fma_f32 v[110:111], v[60:61], v[52:53], v[110:111] op_sel_hi:[1,0,1]
	v_pk_fma_f32 v[112:113], v[60:61], v[52:53], v[112:113] op_sel:[0,1,0]
	v_pk_fma_f32 v[144:145], v[60:61], v[54:55], v[144:145] op_sel_hi:[1,0,1]
	v_pk_fma_f32 v[146:147], v[60:61], v[54:55], v[146:147] op_sel:[0,1,0]
	v_pk_fma_f32 v[64:65], v[106:107], v[48:49], v[110:111] op_sel_hi:[1,0,1]
	v_pk_fma_f32 v[66:67], v[106:107], v[48:49], v[112:113] op_sel:[0,1,0]
	v_pk_fma_f32 v[68:69], v[106:107], v[50:51], v[144:145] op_sel_hi:[1,0,1]
	v_pk_fma_f32 v[70:71], v[106:107], v[50:51], v[146:147] op_sel:[0,1,0]
	s_waitcnt lgkmcnt(0)
	ds_read_b128 v[40:43], v175 offset:38400
	ds_read_b128 v[44:47], v175 offset:38416
	ds_read_b128 v[48:51], v175 offset:38432
	ds_read_b128 v[52:55], v175 offset:38448
	ds_read_b128 v[56:59], v175 offset:38464
	ds_read_b128 v[60:63], v123 offset:48640
	v_pk_mul_f32 v[106:107], v[64:65], v[76:77] op_sel_hi:[1,0]
	v_pk_mul_f32 v[108:109], v[64:65], v[88:89] op_sel_hi:[1,0]
	v_pk_fma_f32 v[106:107], v[66:67], v[76:77], v[106:107] op_sel:[0,1,0]
	v_pk_fma_f32 v[108:109], v[66:67], v[88:89], v[108:109] op_sel:[0,1,0]
	v_pk_fma_f32 v[106:107], v[68:69], v[78:79], v[106:107] op_sel_hi:[1,0,1]
	v_pk_fma_f32 v[108:109], v[68:69], v[90:91], v[108:109] op_sel_hi:[1,0,1]
	v_pk_fma_f32 v[106:107], v[70:71], v[78:79], v[106:107] op_sel:[0,1,0]
	v_pk_fma_f32 v[108:109], v[70:71], v[90:91], v[108:109] op_sel:[0,1,0]
	v_pk_mul_f32 v[110:111], v[64:65], v[72:73] op_sel_hi:[1,0]
	v_add_f32_dpp v106, v106, v106 quad_perm:[1,0,3,2] row_mask:0xf bank_mask:0xf bound_ctrl:1
	v_add_f32_dpp v107, v107, v107 quad_perm:[1,0,3,2] row_mask:0xf bank_mask:0xf bound_ctrl:1
	v_pk_fma_f32 v[108:109], v[94:95], v[176:177], v[108:109]
	v_pk_mul_f32 v[112:113], v[66:67], v[72:73] op_sel:[0,1]
	v_add_f32_dpp v106, v106, v106 quad_perm:[2,3,0,1] row_mask:0xf bank_mask:0xf bound_ctrl:1
	v_add_f32_dpp v107, v107, v107 quad_perm:[2,3,0,1] row_mask:0xf bank_mask:0xf bound_ctrl:1
	v_add_f32_dpp v149, v108, v108 row_half_mirror row_mask:0xf bank_mask:0xf bound_ctrl:1
	v_add_f32_dpp v149, v109, v109 row_half_mirror row_mask:0xf bank_mask:0xa
	v_add_f32_dpp v106, v106, v106 row_half_mirror row_mask:0xf bank_mask:0xf bound_ctrl:1
	v_add_f32_dpp v107, v107, v107 row_half_mirror row_mask:0xf bank_mask:0xf bound_ctrl:1
	v_pk_mul_f32 v[144:145], v[68:69], v[74:75] op_sel_hi:[1,0]
	v_pk_mul_f32 v[146:147], v[70:71], v[74:75] op_sel:[0,1]
	v_add_f32_dpp v150, v148, v148 row_ror:8 row_mask:0xf bank_mask:0xf bound_ctrl:1
	v_add_f32_dpp v150, v149, v149 row_ror:8 row_mask:0xf bank_mask:0xc
	v_add_f32_dpp v106, v106, v106 row_mirror row_mask:0xf bank_mask:0xf bound_ctrl:1
	v_add_f32_dpp v107, v107, v107 row_mirror row_mask:0xf bank_mask:0xf bound_ctrl:1
	v_pk_fma_f32 v[110:111], v[92:93], v[84:85], v[110:111] op_sel_hi:[1,0,1]
	v_pk_fma_f32 v[112:113], v[92:93], v[84:85], v[112:113] op_sel:[0,1,0]
	v_pk_fma_f32 v[144:145], v[92:93], v[86:87], v[144:145] op_sel_hi:[1,0,1]
	v_pk_fma_f32 v[146:147], v[92:93], v[86:87], v[146:147] op_sel:[0,1,0]
	v_add_f32_dpp v150, v150, v150 quad_perm:[1,0,3,2] row_mask:0xf bank_mask:0xf bound_ctrl:1
	v_pk_fma_f32 v[64:65], v[106:107], v[80:81], v[110:111] op_sel_hi:[1,0,1]
	v_pk_fma_f32 v[66:67], v[106:107], v[80:81], v[112:113] op_sel:[0,1,0]
	v_add_f32_dpp v150, v150, v150 quad_perm:[2,3,0,1] row_mask:0xf bank_mask:0xf bound_ctrl:1
	v_pk_fma_f32 v[68:69], v[106:107], v[82:83], v[144:145] op_sel_hi:[1,0,1]
	v_pk_fma_f32 v[70:71], v[106:107], v[82:83], v[146:147] op_sel:[0,1,0]
	ds_write_b32 v178, v150 offset:3584
	s_waitcnt lgkmcnt(1)
; #define SC_GET(X, t) do { const float* p = rec + (t) * 320; w##X = *(const f32x4*)p; a##X = *(const f32x4*)(p + 4); b##X = *(const f32x4*)(p + 8); k##X = *(const f32x4*)(p + 12); q##X = *(const f32x4*)(p + 16); \
;                 v##X = *(const f32x4*)(VVa + (t) * 64); } while (0)
; DI void scan_phase(unsigned char* lds, const Ctx& a, const Op& d, const int variant) {
;     ...
;                 SC_GET(A, 0);
; #pragma unroll 2
;                 for (int t = 0; t < SC_T; t += 2) {
;                     SC_GET(B, t + 1);
;                     SC_STEP(A, t);
;                     if (t + 2 < SC_T) SC_GET(A, t + 2);
;                     SC_STEP(B, t + 1);
;                 }
	ds_read_b128 v[72:75], v175 offset:39680
	ds_read_b128 v[76:79], v175 offset:39696
	ds_read_b128 v[80:83], v175 offset:39712
	ds_read_b128 v[84:87], v175 offset:39728
	ds_read_b128 v[88:91], v175 offset:39744
	ds_read_b128 v[92:95], v123 offset:48896
	v_pk_mul_f32 v[106:107], v[64:65], v[44:45] op_sel_hi:[1,0]
	v_pk_mul_f32 v[108:109], v[64:65], v[56:57] op_sel_hi:[1,0]
	v_pk_fma_f32 v[106:107], v[66:67], v[44:45], v[106:107] op_sel:[0,1,0]
	v_pk_fma_f32 v[108:109], v[66:67], v[56:57], v[108:109] op_sel:[0,1,0]
	v_pk_fma_f32 v[106:107], v[68:69], v[46:47], v[106:107] op_sel_hi:[1,0,1]
	v_pk_fma_f32 v[108:109], v[68:69], v[58:59], v[108:109] op_sel_hi:[1,0,1]
	v_pk_fma_f32 v[106:107], v[70:71], v[46:47], v[106:107] op_sel:[0,1,0]
	v_pk_fma_f32 v[108:109], v[70:71], v[58:59], v[108:109] op_sel:[0,1,0]
	v_pk_mul_f32 v[110:111], v[64:65], v[40:41] op_sel_hi:[1,0]
	v_add_f32_dpp v106, v106, v106 quad_perm:[1,0,3,2] row_mask:0xf bank_mask:0xf bound_ctrl:1
	v_add_f32_dpp v107, v107, v107 quad_perm:[1,0,3,2] row_mask:0xf bank_mask:0xf bound_ctrl:1
	v_pk_fma_f32 v[108:109], v[62:63], v[176:177], v[108:109]
	v_pk_mul_f32 v[112:113], v[66:67], v[40:41] op_sel:[0,1]
	v_add_f32_dpp v106, v106, v106 quad_perm:[2,3,0,1] row_mask:0xf bank_mask:0xf bound_ctrl:1
	v_add_f32_dpp v107, v107, v107 quad_perm:[2,3,0,1] row_mask:0xf bank_mask:0xf bound_ctrl:1
	v_add_f32_dpp v148, v108, v108 row_half_mirror row_mask:0xf bank_mask:0xf bound_ctrl:1
	v_add_f32_dpp v148, v109, v109 row_half_mirror row_mask:0xf bank_mask:0xa
	v_add_f32_dpp v106, v106, v106 row_half_mirror row_mask:0xf bank_mask:0xf bound_ctrl:1
	v_add_f32_dpp v107, v107, v107 row_half_mirror row_mask:0xf bank_mask:0xf bound_ctrl:1
	v_pk_mul_f32 v[144:145], v[68:69], v[42:43] op_sel_hi:[1,0]
	v_pk_mul_f32 v[146:147], v[70:71], v[42:43] op_sel:[0,1]
	v_add_f32_dpp v106, v106, v106 row_mirror row_mask:0xf bank_mask:0xf bound_ctrl:1
	v_add_f32_dpp v107, v107, v107 row_mirror row_mask:0xf bank_mask:0xf bound_ctrl:1
	v_pk_fma_f32 v[110:111], v[60:61], v[52:53], v[110:111] op_sel_hi:[1,0,1]
	v_pk_fma_f32 v[112:113], v[60:61], v[52:53], v[112:113] op_sel:[0,1,0]
	v_pk_fma_f32 v[144:145], v[60:61], v[54:55], v[144:145] op_sel_hi:[1,0,1]
	v_pk_fma_f32 v[146:147], v[60:61], v[54:55], v[146:147] op_sel:[0,1,0]
	v_pk_fma_f32 v[64:65], v[106:107], v[48:49], v[110:111] op_sel_hi:[1,0,1]
	v_pk_fma_f32 v[66:67], v[106:107], v[48:49], v[112:113] op_sel:[0,1,0]
	v_pk_fma_f32 v[68:69], v[106:107], v[50:51], v[144:145] op_sel_hi:[1,0,1]
	v_pk_fma_f32 v[70:71], v[106:107], v[50:51], v[146:147] op_sel:[0,1,0]
	s_waitcnt lgkmcnt(0)
	ds_read_b128 v[40:43], v175 offset:40960
	ds_read_b128 v[44:47], v175 offset:40976
	ds_read_b128 v[48:51], v175 offset:40992
	ds_read_b128 v[52:55], v175 offset:41008
	ds_read_b128 v[56:59], v175 offset:41024
	ds_read_b128 v[60:63], v123 offset:49152
	v_pk_mul_f32 v[106:107], v[64:65], v[76:77] op_sel_hi:[1,0]
	v_pk_mul_f32 v[108:109], v[64:65], v[88:89] op_sel_hi:[1,0]
	v_pk_fma_f32 v[106:107], v[66:67], v[76:77], v[106:107] op_sel:[0,1,0]
	v_pk_fma_f32 v[108:109], v[66:67], v[88:89], v[108:109] op_sel:[0,1,0]
	v_pk_fma_f32 v[106:107], v[68:69], v[78:79], v[106:107] op_sel_hi:[1,0,1]
	v_pk_fma_f32 v[108:109], v[68:69], v[90:91], v[108:109] op_sel_hi:[1,0,1]
	v_pk_fma_f32 v[106:107], v[70:71], v[78:79], v[106:107] op_sel:[0,1,0]
	v_pk_fma_f32 v[108:109], v[70:71], v[90:91], v[108:109] op_sel:[0,1,0]
	v_pk_mul_f32 v[110:111], v[64:65], v[72:73] op_sel_hi:[1,0]
	v_add_f32_dpp v106, v106, v106 quad_perm:[1,0,3,2] row_mask:0xf bank_mask:0xf bound_ctrl:1
	v_add_f32_dpp v107, v107, v107 quad_perm:[1,0,3,2] row_mask:0xf bank_mask:0xf bound_ctrl:1
	v_pk_fma_f32 v[108:109], v[94:95], v[176:177], v[108:109]
	v_pk_mul_f32 v[112:113], v[66:67], v[72:73] op_sel:[0,1]
	v_add_f32_dpp v106, v106, v106 quad_perm:[2,3,0,1] row_mask:0xf bank_mask:0xf bound_ctrl:1
	v_add_f32_dpp v107, v107, v107 quad_perm:[2,3,0,1] row_mask:0xf bank_mask:0xf bound_ctrl:1
	v_add_f32_dpp v149, v108, v108 row_half_mirror row_mask:0xf bank_mask:0xf bound_ctrl:1
	v_add_f32_dpp v149, v109, v109 row_half_mirror row_mask:0xf bank_mask:0xa
	v_add_f32_dpp v106, v106, v106 row_half_mirror row_mask:0xf bank_mask:0xf bound_ctrl:1
	v_add_f32_dpp v107, v107, v107 row_half_mirror row_mask:0xf bank_mask:0xf bound_ctrl:1
	v_pk_mul_f32 v[144:145], v[68:69], v[74:75] op_sel_hi:[1,0]
	v_pk_mul_f32 v[146:147], v[70:71], v[74:75] op_sel:[0,1]
	v_add_f32_dpp v150, v148, v148 row_ror:8 row_mask:0xf bank_mask:0xf bound_ctrl:1
	v_add_f32_dpp v150, v149, v149 row_ror:8 row_mask:0xf bank_mask:0xc
	v_add_f32_dpp v106, v106, v106 row_mirror row_mask:0xf bank_mask:0xf bound_ctrl:1
	v_add_f32_dpp v107, v107, v107 row_mirror row_mask:0xf bank_mask:0xf bound_ctrl:1
	v_pk_fma_f32 v[110:111], v[92:93], v[84:85], v[110:111] op_sel_hi:[1,0,1]
	v_pk_fma_f32 v[112:113], v[92:93], v[84:85], v[112:113] op_sel:[0,1,0]
	v_pk_fma_f32 v[144:145], v[92:93], v[86:87], v[144:145] op_sel_hi:[1,0,1]
	v_pk_fma_f32 v[146:147], v[92:93], v[86:87], v[146:147] op_sel:[0,1,0]
	v_add_f32_dpp v150, v150, v150 quad_perm:[1,0,3,2] row_mask:0xf bank_mask:0xf bound_ctrl:1
	v_pk_fma_f32 v[64:65], v[106:107], v[80:81], v[110:111] op_sel_hi:[1,0,1]
	v_pk_fma_f32 v[66:67], v[106:107], v[80:81], v[112:113] op_sel:[0,1,0]
	v_add_f32_dpp v150, v150, v150 quad_perm:[2,3,0,1] row_mask:0xf bank_mask:0xf bound_ctrl:1
	v_pk_fma_f32 v[68:69], v[106:107], v[82:83], v[144:145] op_sel_hi:[1,0,1]
	v_pk_fma_f32 v[70:71], v[106:107], v[82:83], v[146:147] op_sel:[0,1,0]
	ds_write_b32 v178, v150 offset:3840
	s_setprio 0
